# GEMM main loops without the per-segment s_setprio toggling
# speedup vs baseline: 1.0086x; 1.0086x over previous
; #define PG8_STAGE(bufoff, gbase, voff) do { _Pragma("unroll") for (int _i = 0; _i < 2; ++_i) \
;         __builtin_amdgcn_global_load_lds((const unsigned*)((const char*)(gbase) + (voff)[_i]), (PG8_LAS unsigned*)(lds + (bufoff) + ldsw + _i * 8192), 16, 0, 0); } while (0)
; #define PG8_LDA(dst, b, h) do { _Pragma("unroll") for (int m = 0; m < 4; ++m) _Pragma("unroll") for (int k = 0; k < 2; ++k) dst[m][k] = *(const PG8_LAS bf16x8*)(lds + PG8_SA(b, h) + aoff + m * 2048 + k * 1024); } while (0)
; #define PG8_LDB(dst, b, h) do { _Pragma("unroll") for (int n = 0; n < 2; ++n) _Pragma("unroll") for (int k = 0; k < 2; ++k) dst[n][k] = *(const PG8_LAS bf16x8*)(lds + (SP2 ? PG8_SB(b, hw) + (h) * 4096 : PG8_SB(b, h)) + boff + n * 2048 + k * 1024); } while (0)
; #define PG8_WAIT_V(n) asm volatile("s_waitcnt vmcnt(" #n ")" ::: "memory")
; #define PG8_WAIT_L(n) asm volatile("s_waitcnt lgkmcnt(" #n ")" ::: "memory")
; #define PG8_BAR __builtin_amdgcn_s_barrier()
; #define PG8_SCHED __builtin_amdgcn_sched_barrier(0)
; template <class Epi, class Sched, bool ALIGN_EPI = false, bool SP2 = false, bool F8 = false>
; __device__ __forceinline__ void gemm_phase(PG8_LAS unsigned char* lds, const Gemm g, const Sched& S, const Epi& E, int wv) {
;     ...
;             PG8_LDB(B0, 0, 0); PG8_LDB(B1, 0, 1); PG8_SCHED; PG8_LDA(At, 0, 0); PG8_STAGE(PG8_SA(1, 1), a1 + hstepA, voffA);
;             PG8_WAIT_V(8); PG8_WAIT_L(0); PG8_BAR; PG8_MMA(0, 0, At, B0); PG8_MMA(0, 1, At, B1); PG8_BAR; PG8_SCHED;
;             PG8_LDA(At, 0, 1); PG8_STAGE(PG8_SB(0, 0), b2, voffB); PG8_STAGE(PG8_SB(0, 1), b2 + hstepB, voffB); PG8_STAGE(PG8_SA(0, 0), a2, voffA);
;             PG8_WAIT_V(8); PG8_WAIT_L(0); PG8_BAR; PG8_MMA(1, 0, At, B0); PG8_MMA(1, 1, At, B1); PG8_BAR; PG8_SCHED;
.LBB0_239:
	v_add_u32_e32 v149, s45, v146
	ds_read_b128 v[140:143], v149
	ds_read_b128 v[150:153], v149 offset:1024
	ds_read_b128 v[154:157], v149 offset:2048
	ds_read_b128 v[158:161], v149 offset:3072
	v_add_u32_e32 v149, s46, v146
	ds_read_b128 v[162:165], v149
	ds_read_b128 v[166:169], v149 offset:1024
	ds_read_b128 v[170:173], v149 offset:2048
	ds_read_b128 v[174:177], v149 offset:3072
	s_add_u32 s22, s20, 0xfff80080
	s_addc_u32 s23, s21, -1
	s_cmp_eq_u32 s61, 28
	s_cselect_b32 s25, s15, s23
	s_cselect_b32 s24, s57, s22
	s_cselect_b32 s23, s13, s60
	s_cselect_b32 s22, s58, s59
	v_lshl_add_u64 v[208:209], s[20:21], 0, v[136:137]
	s_add_i32 m0, s29, 0xc000
	ds_read_b128 v[178:181], v148
	ds_read_b128 v[182:185], v148 offset:1024
	ds_read_b128 v[186:189], v148 offset:2048
	ds_read_b128 v[190:193], v148 offset:3072
	ds_read_b128 v[194:197], v148 offset:4096
	ds_read_b128 v[198:201], v148 offset:5120
	ds_read_b128 v[202:205], v148 offset:6144
	ds_read_b128 v[214:217], v148 offset:7168
	global_load_lds_dwordx4 v[208:209], off
	v_lshl_add_u64 v[208:209], s[20:21], 0, v[138:139]
	s_add_i32 m0, s29, 0xe000
	s_nop 0
	global_load_lds_dwordx4 v[208:209], off
	s_waitcnt vmcnt(8)
	s_waitcnt lgkmcnt(0)
	s_barrier
	s_waitcnt lgkmcnt(0)
	v_mfma_f32_16x16x32_bf16 v[124:127], v[140:143], v[178:181], v[124:127]
	v_mfma_f32_16x16x32_bf16 v[120:123], v[154:157], v[178:181], v[120:123]
	v_mfma_f32_16x16x32_bf16 v[116:119], v[140:143], v[186:189], v[116:119]
	v_mfma_f32_16x16x32_bf16 v[108:111], v[154:157], v[186:189], v[108:111]
	v_mfma_f32_16x16x32_bf16 v[100:103], v[140:143], v[194:197], v[100:103]
	v_mfma_f32_16x16x32_bf16 v[92:95], v[154:157], v[194:197], v[92:95]
	v_mfma_f32_16x16x32_bf16 v[84:87], v[140:143], v[202:205], v[84:87]
	v_mfma_f32_16x16x32_bf16 v[76:79], v[154:157], v[202:205], v[76:79]
	v_mfma_f32_16x16x32_bf16 v[124:127], v[150:153], v[182:185], v[124:127]
	v_mfma_f32_16x16x32_bf16 v[120:123], v[158:161], v[182:185], v[120:123]
	v_mfma_f32_16x16x32_bf16 v[116:119], v[150:153], v[190:193], v[116:119]
	v_mfma_f32_16x16x32_bf16 v[108:111], v[158:161], v[190:193], v[108:111]
	v_mfma_f32_16x16x32_bf16 v[100:103], v[150:153], v[198:201], v[100:103]
	v_mfma_f32_16x16x32_bf16 v[92:95], v[158:161], v[198:201], v[92:95]
	v_mfma_f32_16x16x32_bf16 v[84:87], v[150:153], v[214:217], v[84:87]
	v_mfma_f32_16x16x32_bf16 v[76:79], v[158:161], v[214:217], v[76:79]
	v_mfma_f32_16x16x32_bf16 v[112:115], v[162:165], v[178:181], v[112:115]
	v_mfma_f32_16x16x32_bf16 v[104:107], v[170:173], v[178:181], v[104:107]
	v_mfma_f32_16x16x32_bf16 v[96:99], v[162:165], v[186:189], v[96:99]
	v_mfma_f32_16x16x32_bf16 v[88:91], v[170:173], v[186:189], v[88:91]
	v_mfma_f32_16x16x32_bf16 v[80:83], v[162:165], v[194:197], v[80:83]
	v_mfma_f32_16x16x32_bf16 v[72:75], v[170:173], v[194:197], v[72:75]
	v_mfma_f32_16x16x32_bf16 v[68:71], v[162:165], v[202:205], v[68:71]
	v_mfma_f32_16x16x32_bf16 v[64:67], v[170:173], v[202:205], v[64:67]
	v_mfma_f32_16x16x32_bf16 v[112:115], v[166:169], v[182:185], v[112:115]
	v_mfma_f32_16x16x32_bf16 v[104:107], v[174:177], v[182:185], v[104:107]
	v_mfma_f32_16x16x32_bf16 v[96:99], v[166:169], v[190:193], v[96:99]
	v_mfma_f32_16x16x32_bf16 v[88:91], v[174:177], v[190:193], v[88:91]
	v_mfma_f32_16x16x32_bf16 v[80:83], v[166:169], v[198:201], v[80:83]
	v_mfma_f32_16x16x32_bf16 v[72:75], v[174:177], v[198:201], v[72:75]
	v_mfma_f32_16x16x32_bf16 v[68:71], v[166:169], v[214:217], v[68:71]
	v_mfma_f32_16x16x32_bf16 v[64:67], v[174:177], v[214:217], v[64:67]
	s_barrier
	s_mov_b32 m0, s30
	v_lshl_add_u64 v[208:209], s[22:23], 0, v[128:129]
	s_add_u32 s62, s22, 0x80000
	ds_read_b128 v[178:181], v148 offset:16384
	ds_read_b128 v[182:185], v148 offset:17408
	ds_read_b128 v[186:189], v148 offset:18432
	ds_read_b128 v[190:193], v148 offset:19456
	ds_read_b128 v[194:197], v148 offset:20480
	ds_read_b128 v[198:201], v148 offset:21504
	ds_read_b128 v[202:205], v148 offset:22528
	ds_read_b128 v[214:217], v148 offset:23552
	global_load_lds_dwordx4 v[208:209], off
	v_lshl_add_u64 v[210:211], s[22:23], 0, v[130:131]
	s_mov_b32 m0, s31
	s_addc_u32 s63, s23, 0
	global_load_lds_dwordx4 v[210:211], off
	v_lshl_add_u64 v[218:219], s[62:63], 0, v[128:129]
	s_mov_b32 m0, s34
	v_lshl_add_u64 v[220:221], s[24:25], 0, v[132:133]
	global_load_lds_dwordx4 v[218:219], off
	v_lshl_add_u64 v[218:219], s[62:63], 0, v[130:131]
	s_mov_b32 m0, s35
	s_nop 0
	global_load_lds_dwordx4 v[218:219], off
	v_lshl_add_u64 v[218:219], s[24:25], 0, v[134:135]
	s_mov_b32 m0, s29
	s_nop 0
	global_load_lds_dwordx4 v[218:219], off
	s_mov_b32 m0, s36
	s_nop 0
	global_load_lds_dwordx4 v[220:221], off
	s_waitcnt vmcnt(8)
	s_waitcnt lgkmcnt(0)
	s_barrier
; #define PG8_STAGE(bufoff, gbase, voff) do { _Pragma("unroll") for (int _i = 0; _i < 2; ++_i) \
;         __builtin_amdgcn_global_load_lds((const unsigned*)((const char*)(gbase) + (voff)[_i]), (PG8_LAS unsigned*)(lds + (bufoff) + ldsw + _i * 8192), 16, 0, 0); } while (0)
; #define PG8_LDA(dst, b, h) do { _Pragma("unroll") for (int m = 0; m < 4; ++m) _Pragma("unroll") for (int k = 0; k < 2; ++k) dst[m][k] = *(const PG8_LAS bf16x8*)(lds + PG8_SA(b, h) + aoff + m * 2048 + k * 1024); } while (0)
; #define PG8_LDB(dst, b, h) do { _Pragma("unroll") for (int n = 0; n < 2; ++n) _Pragma("unroll") for (int k = 0; k < 2; ++k) dst[n][k] = *(const PG8_LAS bf16x8*)(lds + (SP2 ? PG8_SB(b, hw) + (h) * 4096 : PG8_SB(b, h)) + boff + n * 2048 + k * 1024); } while (0)
; #define PG8_WAIT_V(n) asm volatile("s_waitcnt vmcnt(" #n ")" ::: "memory")
; #define PG8_WAIT_L(n) asm volatile("s_waitcnt lgkmcnt(" #n ")" ::: "memory")
; #define PG8_BAR __builtin_amdgcn_s_barrier()
; #define PG8_SCHED __builtin_amdgcn_sched_barrier(0)
; template <class Epi, class Sched, bool ALIGN_EPI = false, bool SP2 = false, bool F8 = false>
; __device__ __forceinline__ void gemm_phase(PG8_LAS unsigned char* lds, const Gemm g, const Sched& S, const Epi& E, int wv) {
;     ...
;             PG8_WAIT_V(8); PG8_WAIT_L(0); PG8_BAR; PG8_MMA(1, 0, At, B0); PG8_MMA(1, 1, At, B1); PG8_BAR; PG8_SCHED;
;             PG8_LDB(B0, 1, 0); PG8_LDB(B1, 1, 1); PG8_SCHED; PG8_LDA(At, 1, 0); PG8_STAGE(PG8_SA(0, 1), a2 + hstepA, voffA);
;             PG8_WAIT_V(8); PG8_WAIT_L(0); PG8_BAR; PG8_MMA(0, 0, At, B0); PG8_MMA(0, 1, At, B1); PG8_BAR; PG8_SCHED;
	s_waitcnt lgkmcnt(0)
	v_mfma_f32_16x16x32_bf16 v[60:63], v[140:143], v[178:181], v[60:63]
	v_mfma_f32_16x16x32_bf16 v[56:59], v[154:157], v[178:181], v[56:59]
	v_mfma_f32_16x16x32_bf16 v[52:55], v[140:143], v[186:189], v[52:55]
	v_mfma_f32_16x16x32_bf16 v[44:47], v[154:157], v[186:189], v[44:47]
	v_mfma_f32_16x16x32_bf16 v[36:39], v[140:143], v[194:197], v[36:39]
	v_mfma_f32_16x16x32_bf16 v[28:31], v[154:157], v[194:197], v[28:31]
	v_mfma_f32_16x16x32_bf16 v[20:23], v[140:143], v[202:205], v[20:23]
	v_mfma_f32_16x16x32_bf16 v[12:15], v[154:157], v[202:205], v[12:15]
	v_mfma_f32_16x16x32_bf16 v[60:63], v[150:153], v[182:185], v[60:63]
	v_mfma_f32_16x16x32_bf16 v[56:59], v[158:161], v[182:185], v[56:59]
	v_mfma_f32_16x16x32_bf16 v[52:55], v[150:153], v[190:193], v[52:55]
	v_mfma_f32_16x16x32_bf16 v[44:47], v[158:161], v[190:193], v[44:47]
	v_mfma_f32_16x16x32_bf16 v[36:39], v[150:153], v[198:201], v[36:39]
	v_mfma_f32_16x16x32_bf16 v[28:31], v[158:161], v[198:201], v[28:31]
	v_mfma_f32_16x16x32_bf16 v[20:23], v[150:153], v[214:217], v[20:23]
	v_mfma_f32_16x16x32_bf16 v[12:15], v[158:161], v[214:217], v[12:15]
	v_mfma_f32_16x16x32_bf16 v[48:51], v[162:165], v[178:181], v[48:51]
	v_mfma_f32_16x16x32_bf16 v[40:43], v[170:173], v[178:181], v[40:43]
	v_mfma_f32_16x16x32_bf16 v[32:35], v[162:165], v[186:189], v[32:35]
	v_mfma_f32_16x16x32_bf16 v[24:27], v[170:173], v[186:189], v[24:27]
	v_mfma_f32_16x16x32_bf16 v[16:19], v[162:165], v[194:197], v[16:19]
	v_mfma_f32_16x16x32_bf16 v[8:11], v[170:173], v[194:197], v[8:11]
	v_mfma_f32_16x16x32_bf16 v[4:7], v[162:165], v[202:205], v[4:7]
	v_mfma_f32_16x16x32_bf16 v[0:3], v[170:173], v[202:205], v[0:3]
	v_mfma_f32_16x16x32_bf16 v[48:51], v[166:169], v[182:185], v[48:51]
	v_mfma_f32_16x16x32_bf16 v[40:43], v[174:177], v[182:185], v[40:43]
	v_mfma_f32_16x16x32_bf16 v[32:35], v[166:169], v[190:193], v[32:35]
	v_mfma_f32_16x16x32_bf16 v[24:27], v[174:177], v[190:193], v[24:27]
	v_mfma_f32_16x16x32_bf16 v[16:19], v[166:169], v[198:201], v[16:19]
	v_mfma_f32_16x16x32_bf16 v[8:11], v[174:177], v[198:201], v[8:11]
	v_mfma_f32_16x16x32_bf16 v[4:7], v[166:169], v[214:217], v[4:7]
	v_mfma_f32_16x16x32_bf16 v[0:3], v[174:177], v[214:217], v[0:3]
	s_barrier
	v_add_u32_e32 v149, s47, v146
	ds_read_b128 v[140:143], v149
	ds_read_b128 v[150:153], v149 offset:1024
	ds_read_b128 v[154:157], v149 offset:2048
	ds_read_b128 v[158:161], v149 offset:3072
	v_add_u32_e32 v149, s48, v146
	ds_read_b128 v[162:165], v149
	ds_read_b128 v[166:169], v149 offset:1024
	ds_read_b128 v[170:173], v149 offset:2048
	ds_read_b128 v[174:177], v149 offset:3072
	s_add_u32 s24, s24, 0x80000
	s_addc_u32 s25, s25, 0
	s_mov_b32 m0, s37
	v_lshl_add_u64 v[222:223], s[24:25], 0, v[134:135]
	ds_read_b128 v[178:181], v148 offset:32768
	ds_read_b128 v[182:185], v148 offset:33792
	ds_read_b128 v[186:189], v148 offset:34816
	ds_read_b128 v[190:193], v148 offset:35840
	ds_read_b128 v[194:197], v148 offset:36864
	ds_read_b128 v[198:201], v148 offset:37888
	ds_read_b128 v[202:205], v148 offset:38912
	ds_read_b128 v[214:217], v148 offset:39936
	global_load_lds_dwordx4 v[222:223], off
	v_lshl_add_u64 v[222:223], s[24:25], 0, v[132:133]
	s_mov_b32 m0, s38
	s_nop 0
	global_load_lds_dwordx4 v[222:223], off
	s_waitcnt vmcnt(8)
	s_waitcnt lgkmcnt(0)
	s_barrier
	s_waitcnt lgkmcnt(0)
	v_mfma_f32_16x16x32_bf16 v[124:127], v[140:143], v[178:181], v[124:127]
	v_mfma_f32_16x16x32_bf16 v[120:123], v[154:157], v[178:181], v[120:123]
	v_mfma_f32_16x16x32_bf16 v[116:119], v[140:143], v[186:189], v[116:119]
	v_mfma_f32_16x16x32_bf16 v[108:111], v[154:157], v[186:189], v[108:111]
	v_mfma_f32_16x16x32_bf16 v[100:103], v[140:143], v[194:197], v[100:103]
	v_mfma_f32_16x16x32_bf16 v[92:95], v[154:157], v[194:197], v[92:95]
	v_mfma_f32_16x16x32_bf16 v[84:87], v[140:143], v[202:205], v[84:87]
	v_mfma_f32_16x16x32_bf16 v[76:79], v[154:157], v[202:205], v[76:79]
	v_mfma_f32_16x16x32_bf16 v[124:127], v[150:153], v[182:185], v[124:127]
	v_mfma_f32_16x16x32_bf16 v[120:123], v[158:161], v[182:185], v[120:123]
	v_mfma_f32_16x16x32_bf16 v[116:119], v[150:153], v[190:193], v[116:119]
	v_mfma_f32_16x16x32_bf16 v[108:111], v[158:161], v[190:193], v[108:111]
	v_mfma_f32_16x16x32_bf16 v[100:103], v[150:153], v[198:201], v[100:103]
	v_mfma_f32_16x16x32_bf16 v[92:95], v[158:161], v[198:201], v[92:95]
	v_mfma_f32_16x16x32_bf16 v[84:87], v[150:153], v[214:217], v[84:87]
	v_mfma_f32_16x16x32_bf16 v[76:79], v[158:161], v[214:217], v[76:79]
	v_mfma_f32_16x16x32_bf16 v[112:115], v[162:165], v[178:181], v[112:115]
	v_mfma_f32_16x16x32_bf16 v[104:107], v[170:173], v[178:181], v[104:107]
	v_mfma_f32_16x16x32_bf16 v[96:99], v[162:165], v[186:189], v[96:99]
	v_mfma_f32_16x16x32_bf16 v[88:91], v[170:173], v[186:189], v[88:91]
	v_mfma_f32_16x16x32_bf16 v[80:83], v[162:165], v[194:197], v[80:83]
	v_mfma_f32_16x16x32_bf16 v[72:75], v[170:173], v[194:197], v[72:75]
	v_mfma_f32_16x16x32_bf16 v[68:71], v[162:165], v[202:205], v[68:71]
	v_mfma_f32_16x16x32_bf16 v[64:67], v[170:173], v[202:205], v[64:67]
	v_mfma_f32_16x16x32_bf16 v[112:115], v[166:169], v[182:185], v[112:115]
	v_mfma_f32_16x16x32_bf16 v[104:107], v[174:177], v[182:185], v[104:107]
	v_mfma_f32_16x16x32_bf16 v[96:99], v[166:169], v[190:193], v[96:99]
	v_mfma_f32_16x16x32_bf16 v[88:91], v[174:177], v[190:193], v[88:91]
	v_mfma_f32_16x16x32_bf16 v[80:83], v[166:169], v[198:201], v[80:83]
	v_mfma_f32_16x16x32_bf16 v[72:75], v[174:177], v[198:201], v[72:75]
	v_mfma_f32_16x16x32_bf16 v[68:71], v[166:169], v[214:217], v[68:71]
	v_mfma_f32_16x16x32_bf16 v[64:67], v[174:177], v[214:217], v[64:67]
	s_barrier
; #define PG8_STAGE(bufoff, gbase, voff) do { _Pragma("unroll") for (int _i = 0; _i < 2; ++_i) \
;         __builtin_amdgcn_global_load_lds((const unsigned*)((const char*)(gbase) + (voff)[_i]), (PG8_LAS unsigned*)(lds + (bufoff) + ldsw + _i * 8192), 16, 0, 0); } while (0)
; #define PG8_LDA(dst, b, h) do { _Pragma("unroll") for (int m = 0; m < 4; ++m) _Pragma("unroll") for (int k = 0; k < 2; ++k) dst[m][k] = *(const PG8_LAS bf16x8*)(lds + PG8_SA(b, h) + aoff + m * 2048 + k * 1024); } while (0)
; #define PG8_WAIT_V(n) asm volatile("s_waitcnt vmcnt(" #n ")" ::: "memory")
; #define PG8_WAIT_L(n) asm volatile("s_waitcnt lgkmcnt(" #n ")" ::: "memory")
; #define PG8_BAR __builtin_amdgcn_s_barrier()
; #define PG8_SCHED __builtin_amdgcn_sched_barrier(0)
; template <class Epi, class Sched, bool ALIGN_EPI = false, bool SP2 = false, bool F8 = false>
; __device__ __forceinline__ void gemm_phase(PG8_LAS unsigned char* lds, const Gemm g, const Sched& S, const Epi& E, int wv) {
;     ...
;             PG8_LDA(At, 1, 1); PG8_STAGE(PG8_SB(1, 0), b3, voffB); PG8_STAGE(PG8_SB(1, 1), b3 + hstepB, voffB); PG8_STAGE(PG8_SA(1, 0), a3, voffA);
;             PG8_WAIT_V(8); PG8_WAIT_L(0); PG8_BAR; PG8_MMA(1, 0, At, B0); PG8_MMA(1, 1, At, B1); PG8_BAR; PG8_SCHED;
	s_mov_b32 m0, s39
	v_lshl_add_u64 v[208:209], v[208:209], 0, s[52:53]
	s_add_u32 s22, s22, 0x80080
	ds_read_b128 v[178:181], v148 offset:49152
	ds_read_b128 v[182:185], v148 offset:50176
	ds_read_b128 v[186:189], v148 offset:51200
	ds_read_b128 v[190:193], v148 offset:52224
	ds_read_b128 v[194:197], v148 offset:53248
	ds_read_b128 v[198:201], v148 offset:54272
	ds_read_b128 v[202:205], v148 offset:55296
	ds_read_b128 v[214:217], v148 offset:56320
	global_load_lds_dwordx4 v[208:209], off
	v_lshl_add_u64 v[208:209], v[210:211], 0, s[52:53]
	s_mov_b32 m0, s40
	s_addc_u32 s23, s23, 0
	global_load_lds_dwordx4 v[208:209], off
	v_lshl_add_u64 v[208:209], s[22:23], 0, v[128:129]
	s_mov_b32 m0, s43
	s_nop 0
	global_load_lds_dwordx4 v[208:209], off
	v_lshl_add_u64 v[208:209], s[22:23], 0, v[130:131]
	s_mov_b32 m0, s44
	s_nop 0
	global_load_lds_dwordx4 v[208:209], off
	v_lshl_add_u64 v[208:209], v[218:219], 0, s[52:53]
	s_mov_b32 m0, s41
	s_nop 0
	global_load_lds_dwordx4 v[208:209], off
	v_lshl_add_u64 v[208:209], v[220:221], 0, s[52:53]
	s_mov_b32 m0, s42
	s_nop 0
	global_load_lds_dwordx4 v[208:209], off
	s_waitcnt vmcnt(8)
	s_waitcnt lgkmcnt(0)
	s_barrier
	s_waitcnt lgkmcnt(0)
	v_mfma_f32_16x16x32_bf16 v[60:63], v[140:143], v[178:181], v[60:63]
	v_mfma_f32_16x16x32_bf16 v[56:59], v[154:157], v[178:181], v[56:59]
	v_mfma_f32_16x16x32_bf16 v[52:55], v[140:143], v[186:189], v[52:55]
	v_mfma_f32_16x16x32_bf16 v[44:47], v[154:157], v[186:189], v[44:47]
	v_mfma_f32_16x16x32_bf16 v[36:39], v[140:143], v[194:197], v[36:39]
	v_mfma_f32_16x16x32_bf16 v[28:31], v[154:157], v[194:197], v[28:31]
	v_mfma_f32_16x16x32_bf16 v[20:23], v[140:143], v[202:205], v[20:23]
	v_mfma_f32_16x16x32_bf16 v[12:15], v[154:157], v[202:205], v[12:15]
	v_mfma_f32_16x16x32_bf16 v[60:63], v[150:153], v[182:185], v[60:63]
	v_mfma_f32_16x16x32_bf16 v[56:59], v[158:161], v[182:185], v[56:59]
	v_mfma_f32_16x16x32_bf16 v[52:55], v[150:153], v[190:193], v[52:55]
	v_mfma_f32_16x16x32_bf16 v[44:47], v[158:161], v[190:193], v[44:47]
	v_mfma_f32_16x16x32_bf16 v[36:39], v[150:153], v[198:201], v[36:39]
	v_mfma_f32_16x16x32_bf16 v[28:31], v[158:161], v[198:201], v[28:31]
	v_mfma_f32_16x16x32_bf16 v[20:23], v[150:153], v[214:217], v[20:23]
	v_mfma_f32_16x16x32_bf16 v[12:15], v[158:161], v[214:217], v[12:15]
	v_mfma_f32_16x16x32_bf16 v[48:51], v[162:165], v[178:181], v[48:51]
	v_mfma_f32_16x16x32_bf16 v[40:43], v[170:173], v[178:181], v[40:43]
	v_mfma_f32_16x16x32_bf16 v[32:35], v[162:165], v[186:189], v[32:35]
	v_mfma_f32_16x16x32_bf16 v[24:27], v[170:173], v[186:189], v[24:27]
	v_mfma_f32_16x16x32_bf16 v[16:19], v[162:165], v[194:197], v[16:19]
	v_mfma_f32_16x16x32_bf16 v[8:11], v[170:173], v[194:197], v[8:11]
	v_mfma_f32_16x16x32_bf16 v[4:7], v[162:165], v[202:205], v[4:7]
	v_mfma_f32_16x16x32_bf16 v[0:3], v[170:173], v[202:205], v[0:3]
	v_mfma_f32_16x16x32_bf16 v[48:51], v[166:169], v[182:185], v[48:51]
	v_mfma_f32_16x16x32_bf16 v[40:43], v[174:177], v[182:185], v[40:43]
	v_mfma_f32_16x16x32_bf16 v[32:35], v[166:169], v[190:193], v[32:35]
	v_mfma_f32_16x16x32_bf16 v[24:27], v[174:177], v[190:193], v[24:27]
	v_mfma_f32_16x16x32_bf16 v[16:19], v[166:169], v[198:201], v[16:19]
	v_mfma_f32_16x16x32_bf16 v[8:11], v[174:177], v[198:201], v[8:11]
	v_mfma_f32_16x16x32_bf16 v[4:7], v[166:169], v[214:217], v[4:7]
	v_mfma_f32_16x16x32_bf16 v[0:3], v[174:177], v[214:217], v[0:3]
	s_barrier
	s_add_i32 s61, s61, 2
	s_add_u32 s20, s20, 0x100
	s_addc_u32 s21, s21, 0
	s_add_u32 s59, s59, 0x100
	s_addc_u32 s60, s60, 0
	s_cmp_gt_u32 s61, 29
	s_cbranch_scc0 .LBB0_239
	s_and_b64 vcc, exec, s[10:11]
	s_cbranch_vccz .LBB0_242
	s_barrier

; #define PG8_STAGE(bufoff, gbase, voff) do { _Pragma("unroll") for (int _i = 0; _i < 2; ++_i) \
;         __builtin_amdgcn_global_load_lds((const unsigned*)((const char*)(gbase) + (voff)[_i]), (PG8_LAS unsigned*)(lds + (bufoff) + ldsw + _i * 8192), 16, 0, 0); } while (0)
; #define PG8_LDA(dst, b, h) do { _Pragma("unroll") for (int m = 0; m < 4; ++m) _Pragma("unroll") for (int k = 0; k < 2; ++k) dst[m][k] = *(const PG8_LAS bf16x8*)(lds + PG8_SA(b, h) + aoff + m * 2048 + k * 1024); } while (0)
; #define PG8_LDB(dst, b, h) do { _Pragma("unroll") for (int n = 0; n < 2; ++n) _Pragma("unroll") for (int k = 0; k < 2; ++k) dst[n][k] = *(const PG8_LAS bf16x8*)(lds + (SP2 ? PG8_SB(b, hw) + (h) * 4096 : PG8_SB(b, h)) + boff + n * 2048 + k * 1024); } while (0)
; #define PG8_WAIT_V(n) asm volatile("s_waitcnt vmcnt(" #n ")" ::: "memory")
; #define PG8_WAIT_L(n) asm volatile("s_waitcnt lgkmcnt(" #n ")" ::: "memory")
; #define PG8_BAR __builtin_amdgcn_s_barrier()
; #define PG8_SCHED __builtin_amdgcn_sched_barrier(0)
; template <class Epi, class Sched, bool ALIGN_EPI = false, bool SP2 = false, bool F8 = false>
; __device__ __forceinline__ void gemm_phase(PG8_LAS unsigned char* lds, const Gemm g, const Sched& S, const Epi& E, int wv) {
;     ...
;             const char* a1 = cA + (size_t)(t + 1) * kstep;
;             const char* a2 = last ? nA : cA + (size_t)(t + 2) * kstep; const char* b2 = last ? nB : cB + (size_t)(t + 2) * kstep;
;             const char* a3 = a2 + kstep; const char* b3 = b2 + kstep;
;             if (last && has_next) S.a_ready(nxt);
;             if constexpr (SP2) {
;             PG8_LDB(B0, 0, 0); PG8_LDB(B1, 0, 1); PG8_SCHED; PG8_LDA(At, 0, 0); PG8_STAGE(PG8_SA(1, 1), a1 + hstepA, voffA);
;             PG8_WAIT_V(8); PG8_WAIT_L(0); PG8_BAR; PG8_MMA(0, 0, At, B0); PG8_MMA(0, 1, At, B1); PG8_BAR; PG8_SCHED;
;             PG8_LDA(At, 0, 1); PG8_STAGE(PG8_SB(0, 0), b2, voffB); PG8_STAGE(PG8_SB(0, 1), b2 + hstepB, voffB); PG8_STAGE(PG8_SA(0, 0), a2, voffA);
;             PG8_WAIT_V(8); PG8_WAIT_L(0); PG8_BAR; PG8_MMA(1, 0, At, B0); PG8_MMA(1, 1, At, B1); PG8_BAR; PG8_SCHED;
.LBB0_286:
	v_add_u32_e32 v0, s59, v181
	v_add_u32_e32 v4, s60, v181
	ds_read_b128 v[24:27], v0
	ds_read_b128 v[28:31], v0 offset:1024
	ds_read_b128 v[16:19], v0 offset:2048
	ds_read_b128 v[20:23], v0 offset:3072
	ds_read_b128 v[8:11], v4
	ds_read_b128 v[12:15], v4 offset:1024
	ds_read_b128 v[0:3], v4 offset:2048
	ds_read_b128 v[4:7], v4 offset:3072
	s_add_u32 s28, s26, 0xfffc0080
	s_addc_u32 s29, s27, -1
	s_cmp_eq_u32 s71, 12
	s_cselect_b32 s31, s13, s29
	s_cselect_b32 s30, s17, s28
	s_cselect_b32 s29, s15, s70
	s_cselect_b32 s28, s67, s69
	v_lshl_add_u64 v[200:201], s[26:27], 0, v[168:169]
	s_add_i32 m0, s19, 0xc000
	ds_read_b128 v[172:175], v183
	ds_read_b128 v[176:179], v183 offset:1024
	ds_read_b128 v[184:187], v183 offset:2048
	ds_read_b128 v[188:191], v183 offset:3072
	ds_read_b128 v[192:195], v183 offset:4096
	ds_read_b128 v[196:199], v183 offset:5120
	ds_read_b128 v[214:217], v183 offset:6144
	ds_read_b128 v[218:221], v183 offset:7168
	global_load_lds_dwordx4 v[200:201], off
	v_lshl_add_u64 v[200:201], s[26:27], 0, v[170:171]
	s_add_i32 m0, s19, 0xe000
	s_nop 0
	global_load_lds_dwordx4 v[200:201], off
	s_waitcnt vmcnt(8)
	s_waitcnt lgkmcnt(0)
	s_barrier
	s_waitcnt lgkmcnt(0)
	v_mfma_f32_16x16x128_f8f6f4 v[158:161], v[24:31], v[172:179], v[158:161]
	v_mfma_f32_16x16x128_f8f6f4 v[154:157], v[16:23], v[172:179], v[154:157]
	v_mfma_f32_16x16x128_f8f6f4 v[146:149], v[24:31], v[184:191], v[146:149]
	v_mfma_f32_16x16x128_f8f6f4 v[138:141], v[16:23], v[184:191], v[138:141]
	v_mfma_f32_16x16x128_f8f6f4 v[130:133], v[24:31], v[192:199], v[130:133]
	v_mfma_f32_16x16x128_f8f6f4 v[120:123], v[16:23], v[192:199], v[120:123]
	v_mfma_f32_16x16x128_f8f6f4 v[112:115], v[24:31], v[214:221], v[112:115]
	v_mfma_f32_16x16x128_f8f6f4 v[104:107], v[16:23], v[214:221], v[104:107]
	v_mfma_f32_16x16x128_f8f6f4 v[150:153], v[8:15], v[172:179], v[150:153]
	v_mfma_f32_16x16x128_f8f6f4 v[142:145], v[0:7], v[172:179], v[142:145]
	v_mfma_f32_16x16x128_f8f6f4 v[134:137], v[8:15], v[184:191], v[134:137]
	v_mfma_f32_16x16x128_f8f6f4 v[124:127], v[0:7], v[184:191], v[124:127]
	v_mfma_f32_16x16x128_f8f6f4 v[116:119], v[8:15], v[192:199], v[116:119]
	v_mfma_f32_16x16x128_f8f6f4 v[108:111], v[0:7], v[192:199], v[108:111]
	v_mfma_f32_16x16x128_f8f6f4 v[100:103], v[8:15], v[214:221], v[100:103]
	v_mfma_f32_16x16x128_f8f6f4 v[96:99], v[0:7], v[214:221], v[96:99]
	s_barrier
	s_mov_b32 m0, s40
	v_lshl_add_u64 v[172:173], s[28:29], 0, v[128:129]
	s_add_u32 s72, s28, 0x40000
	ds_read_b128 v[184:187], v183 offset:16384
	ds_read_b128 v[188:191], v183 offset:17408
	ds_read_b128 v[192:195], v183 offset:18432
	ds_read_b128 v[196:199], v183 offset:19456
	ds_read_b128 v[214:217], v183 offset:20480
	ds_read_b128 v[218:221], v183 offset:21504
	ds_read_b128 v[222:225], v183 offset:22528
	ds_read_b128 v[226:229], v183 offset:23552
	global_load_lds_dwordx4 v[172:173], off
	v_lshl_add_u64 v[174:175], s[28:29], 0, v[166:167]
	s_mov_b32 m0, s41
	s_addc_u32 s73, s29, 0
	global_load_lds_dwordx4 v[174:175], off
	v_lshl_add_u64 v[176:177], s[72:73], 0, v[128:129]
	s_mov_b32 m0, s42
	v_lshl_add_u64 v[178:179], s[30:31], 0, v[164:165]
	global_load_lds_dwordx4 v[176:177], off
	v_lshl_add_u64 v[176:177], s[72:73], 0, v[166:167]
	s_mov_b32 m0, s43
	s_nop 0
	global_load_lds_dwordx4 v[176:177], off
	v_lshl_add_u64 v[176:177], s[30:31], 0, v[162:163]
	s_mov_b32 m0, s19
	s_nop 0
	global_load_lds_dwordx4 v[176:177], off
	s_mov_b32 m0, s44
	s_nop 0
	global_load_lds_dwordx4 v[178:179], off
	s_waitcnt vmcnt(8)
	s_waitcnt lgkmcnt(0)
	s_barrier
	s_waitcnt lgkmcnt(0)
	v_mfma_f32_16x16x128_f8f6f4 v[92:95], v[24:31], v[184:191], v[92:95]
	v_mfma_f32_16x16x128_f8f6f4 v[88:91], v[16:23], v[184:191], v[88:91]
	v_mfma_f32_16x16x128_f8f6f4 v[80:83], v[24:31], v[192:199], v[80:83]
	v_mfma_f32_16x16x128_f8f6f4 v[72:75], v[16:23], v[192:199], v[72:75]
	v_mfma_f32_16x16x128_f8f6f4 v[64:67], v[24:31], v[214:221], v[64:67]
	v_mfma_f32_16x16x128_f8f6f4 v[56:59], v[16:23], v[214:221], v[56:59]
	v_mfma_f32_16x16x128_f8f6f4 v[48:51], v[24:31], v[222:229], v[48:51]
	v_mfma_f32_16x16x128_f8f6f4 v[40:43], v[16:23], v[222:229], v[40:43]
	v_mfma_f32_16x16x128_f8f6f4 v[84:87], v[8:15], v[184:191], v[84:87]
	v_mfma_f32_16x16x128_f8f6f4 v[76:79], v[0:7], v[184:191], v[76:79]
	v_mfma_f32_16x16x128_f8f6f4 v[68:71], v[8:15], v[192:199], v[68:71]
	v_mfma_f32_16x16x128_f8f6f4 v[60:63], v[0:7], v[192:199], v[60:63]
	v_mfma_f32_16x16x128_f8f6f4 v[52:55], v[8:15], v[214:221], v[52:55]
	v_mfma_f32_16x16x128_f8f6f4 v[44:47], v[0:7], v[214:221], v[44:47]
	v_mfma_f32_16x16x128_f8f6f4 v[36:39], v[8:15], v[222:229], v[36:39]
	v_mfma_f32_16x16x128_f8f6f4 v[32:35], v[0:7], v[222:229], v[32:35]
	s_barrier
; #define PG8_STAGE(bufoff, gbase, voff) do { _Pragma("unroll") for (int _i = 0; _i < 2; ++_i) \
;         __builtin_amdgcn_global_load_lds((const unsigned*)((const char*)(gbase) + (voff)[_i]), (PG8_LAS unsigned*)(lds + (bufoff) + ldsw + _i * 8192), 16, 0, 0); } while (0)
; #define PG8_LDA(dst, b, h) do { _Pragma("unroll") for (int m = 0; m < 4; ++m) _Pragma("unroll") for (int k = 0; k < 2; ++k) dst[m][k] = *(const PG8_LAS bf16x8*)(lds + PG8_SA(b, h) + aoff + m * 2048 + k * 1024); } while (0)
; #define PG8_LDB(dst, b, h) do { _Pragma("unroll") for (int n = 0; n < 2; ++n) _Pragma("unroll") for (int k = 0; k < 2; ++k) dst[n][k] = *(const PG8_LAS bf16x8*)(lds + (SP2 ? PG8_SB(b, hw) + (h) * 4096 : PG8_SB(b, h)) + boff + n * 2048 + k * 1024); } while (0)
; #define PG8_WAIT_V(n) asm volatile("s_waitcnt vmcnt(" #n ")" ::: "memory")
; #define PG8_WAIT_L(n) asm volatile("s_waitcnt lgkmcnt(" #n ")" ::: "memory")
; #define PG8_BAR __builtin_amdgcn_s_barrier()
; #define PG8_SCHED __builtin_amdgcn_sched_barrier(0)
; template <class Epi, class Sched, bool ALIGN_EPI = false, bool SP2 = false, bool F8 = false>
; __device__ __forceinline__ void gemm_phase(PG8_LAS unsigned char* lds, const Gemm g, const Sched& S, const Epi& E, int wv) {
;     ...
;             PG8_LDB(B0, 1, 0); PG8_LDB(B1, 1, 1); PG8_SCHED; PG8_LDA(At, 1, 0); PG8_STAGE(PG8_SA(0, 1), a2 + hstepA, voffA);
;             PG8_WAIT_V(8); PG8_WAIT_L(0); PG8_BAR; PG8_MMA(0, 0, At, B0); PG8_MMA(0, 1, At, B1); PG8_BAR; PG8_SCHED;
;             PG8_LDA(At, 1, 1); PG8_STAGE(PG8_SB(1, 0), b3, voffB); PG8_STAGE(PG8_SB(1, 1), b3 + hstepB, voffB); PG8_STAGE(PG8_SA(1, 0), a3, voffA);
;             PG8_WAIT_V(8); PG8_WAIT_L(0); PG8_BAR; PG8_MMA(1, 0, At, B0); PG8_MMA(1, 1, At, B1); PG8_BAR; PG8_SCHED;
;     ...
;         if constexpr (F8) asm volatile("s_nop 15\n\ts_nop 15" ::: "memory");
	v_add_u32_e32 v12, s61, v181
	v_add_u32_e32 v28, s62, v181
	ds_read_b128 v[0:3], v12
	ds_read_b128 v[4:7], v12 offset:1024
	ds_read_b128 v[8:11], v12 offset:2048
	ds_read_b128 v[12:15], v12 offset:3072
	ds_read_b128 v[16:19], v28
	ds_read_b128 v[20:23], v28 offset:1024
	ds_read_b128 v[24:27], v28 offset:2048
	ds_read_b128 v[28:31], v28 offset:3072
	s_add_u32 s30, s30, 0x40000
	s_addc_u32 s31, s31, 0
	s_mov_b32 m0, s45
	v_lshl_add_u64 v[200:201], s[30:31], 0, v[162:163]
	ds_read_b128 v[184:187], v183 offset:32768
	ds_read_b128 v[188:191], v183 offset:33792
	ds_read_b128 v[192:195], v183 offset:34816
	ds_read_b128 v[196:199], v183 offset:35840
	ds_read_b128 v[214:217], v183 offset:36864
	ds_read_b128 v[218:221], v183 offset:37888
	ds_read_b128 v[222:225], v183 offset:38912
	ds_read_b128 v[226:229], v183 offset:39936
	global_load_lds_dwordx4 v[200:201], off
	v_lshl_add_u64 v[200:201], s[30:31], 0, v[164:165]
	s_mov_b32 m0, s46
	s_nop 0
	global_load_lds_dwordx4 v[200:201], off
	s_waitcnt vmcnt(8)
	s_waitcnt lgkmcnt(0)
	s_barrier
	s_waitcnt lgkmcnt(0)
	v_mfma_f32_16x16x128_f8f6f4 v[158:161], v[0:7], v[184:191], v[158:161]
	v_mfma_f32_16x16x128_f8f6f4 v[154:157], v[8:15], v[184:191], v[154:157]
	v_mfma_f32_16x16x128_f8f6f4 v[146:149], v[0:7], v[192:199], v[146:149]
	v_mfma_f32_16x16x128_f8f6f4 v[138:141], v[8:15], v[192:199], v[138:141]
	v_mfma_f32_16x16x128_f8f6f4 v[130:133], v[0:7], v[214:221], v[130:133]
	v_mfma_f32_16x16x128_f8f6f4 v[120:123], v[8:15], v[214:221], v[120:123]
	v_mfma_f32_16x16x128_f8f6f4 v[112:115], v[0:7], v[222:229], v[112:115]
	v_mfma_f32_16x16x128_f8f6f4 v[104:107], v[8:15], v[222:229], v[104:107]
	v_mfma_f32_16x16x128_f8f6f4 v[150:153], v[16:23], v[184:191], v[150:153]
	v_mfma_f32_16x16x128_f8f6f4 v[142:145], v[24:31], v[184:191], v[142:145]
	v_mfma_f32_16x16x128_f8f6f4 v[134:137], v[16:23], v[192:199], v[134:137]
	v_mfma_f32_16x16x128_f8f6f4 v[124:127], v[24:31], v[192:199], v[124:127]
	v_mfma_f32_16x16x128_f8f6f4 v[116:119], v[16:23], v[214:221], v[116:119]
	v_mfma_f32_16x16x128_f8f6f4 v[108:111], v[24:31], v[214:221], v[108:111]
	v_mfma_f32_16x16x128_f8f6f4 v[100:103], v[16:23], v[222:229], v[100:103]
	v_mfma_f32_16x16x128_f8f6f4 v[96:99], v[24:31], v[222:229], v[96:99]
	s_barrier
	s_mov_b32 m0, s49
	v_lshl_add_u64 v[172:173], v[172:173], 0, s[52:53]
	s_add_u32 s28, s28, 0x40080
	ds_read_b128 v[184:187], v183 offset:49152
	ds_read_b128 v[188:191], v183 offset:50176
	ds_read_b128 v[192:195], v183 offset:51200
	ds_read_b128 v[196:199], v183 offset:52224
	ds_read_b128 v[214:217], v183 offset:53248
	ds_read_b128 v[218:221], v183 offset:54272
	ds_read_b128 v[222:225], v183 offset:55296
	ds_read_b128 v[226:229], v183 offset:56320
	global_load_lds_dwordx4 v[172:173], off
	v_lshl_add_u64 v[172:173], v[174:175], 0, s[52:53]
	s_mov_b32 m0, s54
	s_addc_u32 s29, s29, 0
	global_load_lds_dwordx4 v[172:173], off
	v_lshl_add_u64 v[172:173], s[28:29], 0, v[128:129]
	s_mov_b32 m0, s57
	s_nop 0
	global_load_lds_dwordx4 v[172:173], off
	v_lshl_add_u64 v[172:173], s[28:29], 0, v[166:167]
	s_mov_b32 m0, s58
	s_nop 0
	global_load_lds_dwordx4 v[172:173], off
	v_lshl_add_u64 v[172:173], v[176:177], 0, s[52:53]
	s_mov_b32 m0, s55
	s_nop 0
	global_load_lds_dwordx4 v[172:173], off
	v_lshl_add_u64 v[172:173], v[178:179], 0, s[52:53]
	s_mov_b32 m0, s56
	s_nop 0
	global_load_lds_dwordx4 v[172:173], off
	s_waitcnt vmcnt(8)
	s_waitcnt lgkmcnt(0)
	s_barrier
	s_waitcnt lgkmcnt(0)
	v_mfma_f32_16x16x128_f8f6f4 v[92:95], v[0:7], v[184:191], v[92:95]
	v_mfma_f32_16x16x128_f8f6f4 v[88:91], v[8:15], v[184:191], v[88:91]
	v_mfma_f32_16x16x128_f8f6f4 v[80:83], v[0:7], v[192:199], v[80:83]
	v_mfma_f32_16x16x128_f8f6f4 v[72:75], v[8:15], v[192:199], v[72:75]
	v_mfma_f32_16x16x128_f8f6f4 v[64:67], v[0:7], v[214:221], v[64:67]
	v_mfma_f32_16x16x128_f8f6f4 v[56:59], v[8:15], v[214:221], v[56:59]
	v_mfma_f32_16x16x128_f8f6f4 v[48:51], v[0:7], v[222:229], v[48:51]
	v_mfma_f32_16x16x128_f8f6f4 v[40:43], v[8:15], v[222:229], v[40:43]
	v_mfma_f32_16x16x128_f8f6f4 v[84:87], v[16:23], v[184:191], v[84:87]
	v_mfma_f32_16x16x128_f8f6f4 v[76:79], v[24:31], v[184:191], v[76:79]
	v_mfma_f32_16x16x128_f8f6f4 v[68:71], v[16:23], v[192:199], v[68:71]
	v_mfma_f32_16x16x128_f8f6f4 v[60:63], v[24:31], v[192:199], v[60:63]
	v_mfma_f32_16x16x128_f8f6f4 v[52:55], v[16:23], v[214:221], v[52:55]
	v_mfma_f32_16x16x128_f8f6f4 v[44:47], v[24:31], v[214:221], v[44:47]
	v_mfma_f32_16x16x128_f8f6f4 v[36:39], v[16:23], v[222:229], v[36:39]
	v_mfma_f32_16x16x128_f8f6f4 v[32:35], v[24:31], v[222:229], v[32:35]
	s_barrier
	s_add_i32 s71, s71, 2
	s_add_u32 s26, s26, 0x100
	s_addc_u32 s27, s27, 0
	s_add_u32 s69, s69, 0x100
	s_addc_u32 s70, s70, 0
	s_cmp_gt_u32 s71, 13
	s_cbranch_scc0 .LBB0_286
	s_nop 15
	s_nop 15
	s_and_b64 vcc, exec, s[8:9]
	s_mov_b32 s17, 0x4a04000
	s_cbranch_vccz .LBB0_289
	s_barrier

; #define PG8_STAGE(bufoff, gbase, voff) do { _Pragma("unroll") for (int _i = 0; _i < 2; ++_i) \
;         __builtin_amdgcn_global_load_lds((const unsigned*)((const char*)(gbase) + (voff)[_i]), (PG8_LAS unsigned*)(lds + (bufoff) + ldsw + _i * 8192), 16, 0, 0); } while (0)
; #define PG8_LDA(dst, b, h) do { _Pragma("unroll") for (int m = 0; m < 4; ++m) _Pragma("unroll") for (int k = 0; k < 2; ++k) dst[m][k] = *(const PG8_LAS bf16x8*)(lds + PG8_SA(b, h) + aoff + m * 2048 + k * 1024); } while (0)
; #define PG8_LDB(dst, b, h) do { _Pragma("unroll") for (int n = 0; n < 2; ++n) _Pragma("unroll") for (int k = 0; k < 2; ++k) dst[n][k] = *(const PG8_LAS bf16x8*)(lds + (SP2 ? PG8_SB(b, hw) + (h) * 4096 : PG8_SB(b, h)) + boff + n * 2048 + k * 1024); } while (0)
; #define PG8_WAIT_V(n) asm volatile("s_waitcnt vmcnt(" #n ")" ::: "memory")
; #define PG8_WAIT_L(n) asm volatile("s_waitcnt lgkmcnt(" #n ")" ::: "memory")
; #define PG8_BAR __builtin_amdgcn_s_barrier()
; #define PG8_SCHED __builtin_amdgcn_sched_barrier(0)
; template <class Epi, class Sched, bool ALIGN_EPI = false, bool SP2 = false, bool F8 = false>
; __device__ __forceinline__ void gemm_phase(PG8_LAS unsigned char* lds, const Gemm g, const Sched& S, const Epi& E, int wv) {
;     ...
;             const char* a1 = cA + (size_t)(t + 1) * kstep;
;             const char* a2 = last ? nA : cA + (size_t)(t + 2) * kstep; const char* b2 = last ? nB : cB + (size_t)(t + 2) * kstep;
;             const char* a3 = a2 + kstep; const char* b3 = b2 + kstep;
;             if (last && has_next) S.a_ready(nxt);
;             if constexpr (SP2) {
;             PG8_LDB(B0, 0, 0); PG8_LDB(B1, 0, 1); PG8_SCHED; PG8_LDA(At, 0, 0); PG8_STAGE(PG8_SA(1, 1), a1 + hstepA, voffA);
;             PG8_WAIT_V(8); PG8_WAIT_L(0); PG8_BAR; PG8_MMA(0, 0, At, B0); PG8_MMA(0, 1, At, B1); PG8_BAR; PG8_SCHED;
;             PG8_LDA(At, 0, 1); PG8_STAGE(PG8_SB(0, 0), b2, voffB); PG8_STAGE(PG8_SB(0, 1), b2 + hstepB, voffB); PG8_STAGE(PG8_SA(0, 0), a2, voffA);
;             PG8_WAIT_V(8); PG8_WAIT_L(0); PG8_BAR; PG8_MMA(1, 0, At, B0); PG8_MMA(1, 1, At, B1); PG8_BAR; PG8_SCHED;
.LBB0_638:
	v_add_u32_e32 v12, s57, v189
	v_add_u32_e32 v28, s58, v189
	s_add_u32 s22, s18, s20
	ds_read_b128 v[0:3], v12
	ds_read_b128 v[4:7], v12 offset:1024
	ds_read_b128 v[8:11], v12 offset:2048
	ds_read_b128 v[12:15], v12 offset:3072
	ds_read_b128 v[16:19], v28
	ds_read_b128 v[20:23], v28 offset:1024
	ds_read_b128 v[24:27], v28 offset:2048
	ds_read_b128 v[28:31], v28 offset:3072
	s_addc_u32 s23, s19, s21
	s_add_u32 s22, s22, 0x100
	s_addc_u32 s23, s23, 0
	s_add_u32 s67, s71, s20
	s_addc_u32 s74, s72, s21
	s_cmpk_eq_i32 s20, 0x700
	s_cselect_b32 s25, s13, s23
	s_cselect_b32 s24, s63, s22
	s_cselect_b32 s23, s65, s74
	s_cselect_b32 s22, s68, s67
	v_lshl_add_u64 v[130:131], v[176:177], 0, s[20:21]
	s_add_i32 m0, s34, 0xc000
	ds_read_b128 v[192:195], v191
	ds_read_b128 v[196:199], v191 offset:1024
	ds_read_b128 v[214:217], v191 offset:2048
	ds_read_b128 v[218:221], v191 offset:3072
	ds_read_b128 v[222:225], v191 offset:4096
	ds_read_b128 v[226:229], v191 offset:5120
	ds_read_b128 v[230:233], v191 offset:6144
	ds_read_b128 v[234:237], v191 offset:7168
	global_load_lds_dwordx4 v[130:131], off
	v_lshl_add_u64 v[130:131], v[178:179], 0, s[20:21]
	s_add_i32 m0, s34, 0xe000
	s_nop 0
	global_load_lds_dwordx4 v[130:131], off
	s_waitcnt vmcnt(8)
	s_waitcnt lgkmcnt(0)
	s_barrier
	s_waitcnt lgkmcnt(0)
	v_mfma_f32_16x16x128_f8f6f4 v[160:163], v[0:7], v[192:199], v[160:163]
	v_mfma_f32_16x16x128_f8f6f4 v[156:159], v[8:15], v[192:199], v[156:159]
	v_mfma_f32_16x16x128_f8f6f4 v[144:147], v[0:7], v[214:221], v[144:147]
	v_mfma_f32_16x16x128_f8f6f4 v[140:143], v[8:15], v[214:221], v[140:143]
	v_mfma_f32_16x16x128_f8f6f4 v[124:127], v[0:7], v[222:229], v[124:127]
	v_mfma_f32_16x16x128_f8f6f4 v[120:123], v[8:15], v[222:229], v[120:123]
	v_mfma_f32_16x16x128_f8f6f4 v[108:111], v[0:7], v[230:237], v[108:111]
	v_mfma_f32_16x16x128_f8f6f4 v[104:107], v[8:15], v[230:237], v[104:107]
	v_mfma_f32_16x16x128_f8f6f4 v[152:155], v[16:23], v[192:199], v[152:155]
	v_mfma_f32_16x16x128_f8f6f4 v[148:151], v[24:31], v[192:199], v[148:151]
	v_mfma_f32_16x16x128_f8f6f4 v[136:139], v[16:23], v[214:221], v[136:139]
	v_mfma_f32_16x16x128_f8f6f4 v[132:135], v[24:31], v[214:221], v[132:135]
	v_mfma_f32_16x16x128_f8f6f4 v[116:119], v[16:23], v[222:229], v[116:119]
	v_mfma_f32_16x16x128_f8f6f4 v[112:115], v[24:31], v[222:229], v[112:115]
	v_mfma_f32_16x16x128_f8f6f4 v[100:103], v[16:23], v[230:237], v[100:103]
	v_mfma_f32_16x16x128_f8f6f4 v[96:99], v[24:31], v[230:237], v[96:99]
	s_barrier
	s_mov_b32 m0, s35
	v_lshl_add_u64 v[130:131], s[22:23], 0, v[168:169]
	s_add_u32 s74, s22, 0x40000
	ds_read_b128 v[192:195], v191 offset:16384
	ds_read_b128 v[196:199], v191 offset:17408
	ds_read_b128 v[214:217], v191 offset:18432
	ds_read_b128 v[218:221], v191 offset:19456
	ds_read_b128 v[222:225], v191 offset:20480
	ds_read_b128 v[226:229], v191 offset:21504
	ds_read_b128 v[230:233], v191 offset:22528
	ds_read_b128 v[234:237], v191 offset:23552
	global_load_lds_dwordx4 v[130:131], off
	v_lshl_add_u64 v[180:181], s[22:23], 0, v[164:165]
	s_mov_b32 m0, s38
	s_addc_u32 s75, s23, 0
	global_load_lds_dwordx4 v[180:181], off
	v_lshl_add_u64 v[182:183], s[74:75], 0, v[168:169]
	s_mov_b32 m0, s39
	v_lshl_add_u64 v[184:185], s[24:25], 0, v[166:167]
	global_load_lds_dwordx4 v[182:183], off
	v_lshl_add_u64 v[182:183], s[74:75], 0, v[164:165]
	s_mov_b32 m0, s40
	s_nop 0
	global_load_lds_dwordx4 v[182:183], off
	v_lshl_add_u64 v[182:183], s[24:25], 0, v[170:171]
	s_mov_b32 m0, s34
	s_nop 0
	global_load_lds_dwordx4 v[182:183], off
	s_mov_b32 m0, s41
	s_nop 0
	global_load_lds_dwordx4 v[184:185], off
	s_waitcnt vmcnt(8)
	s_waitcnt lgkmcnt(0)
	s_barrier
	s_waitcnt lgkmcnt(0)
	v_mfma_f32_16x16x128_f8f6f4 v[92:95], v[0:7], v[192:199], v[92:95]
	v_mfma_f32_16x16x128_f8f6f4 v[88:91], v[8:15], v[192:199], v[88:91]
	v_mfma_f32_16x16x128_f8f6f4 v[76:79], v[0:7], v[214:221], v[76:79]
	v_mfma_f32_16x16x128_f8f6f4 v[72:75], v[8:15], v[214:221], v[72:75]
	v_mfma_f32_16x16x128_f8f6f4 v[60:63], v[0:7], v[222:229], v[60:63]
	v_mfma_f32_16x16x128_f8f6f4 v[56:59], v[8:15], v[222:229], v[56:59]
	v_mfma_f32_16x16x128_f8f6f4 v[44:47], v[0:7], v[230:237], v[44:47]
	v_mfma_f32_16x16x128_f8f6f4 v[40:43], v[8:15], v[230:237], v[40:43]
	v_mfma_f32_16x16x128_f8f6f4 v[84:87], v[16:23], v[192:199], v[84:87]
	v_mfma_f32_16x16x128_f8f6f4 v[80:83], v[24:31], v[192:199], v[80:83]
	v_mfma_f32_16x16x128_f8f6f4 v[68:71], v[16:23], v[214:221], v[68:71]
	v_mfma_f32_16x16x128_f8f6f4 v[64:67], v[24:31], v[214:221], v[64:67]
	v_mfma_f32_16x16x128_f8f6f4 v[52:55], v[16:23], v[222:229], v[52:55]
	v_mfma_f32_16x16x128_f8f6f4 v[48:51], v[24:31], v[222:229], v[48:51]
	v_mfma_f32_16x16x128_f8f6f4 v[36:39], v[16:23], v[230:237], v[36:39]
	v_mfma_f32_16x16x128_f8f6f4 v[32:35], v[24:31], v[230:237], v[32:35]
	s_barrier
; #define PG8_STAGE(bufoff, gbase, voff) do { _Pragma("unroll") for (int _i = 0; _i < 2; ++_i) \
;         __builtin_amdgcn_global_load_lds((const unsigned*)((const char*)(gbase) + (voff)[_i]), (PG8_LAS unsigned*)(lds + (bufoff) + ldsw + _i * 8192), 16, 0, 0); } while (0)
; #define PG8_LDA(dst, b, h) do { _Pragma("unroll") for (int m = 0; m < 4; ++m) _Pragma("unroll") for (int k = 0; k < 2; ++k) dst[m][k] = *(const PG8_LAS bf16x8*)(lds + PG8_SA(b, h) + aoff + m * 2048 + k * 1024); } while (0)
; #define PG8_LDB(dst, b, h) do { _Pragma("unroll") for (int n = 0; n < 2; ++n) _Pragma("unroll") for (int k = 0; k < 2; ++k) dst[n][k] = *(const PG8_LAS bf16x8*)(lds + (SP2 ? PG8_SB(b, hw) + (h) * 4096 : PG8_SB(b, h)) + boff + n * 2048 + k * 1024); } while (0)
; #define PG8_WAIT_V(n) asm volatile("s_waitcnt vmcnt(" #n ")" ::: "memory")
; #define PG8_WAIT_L(n) asm volatile("s_waitcnt lgkmcnt(" #n ")" ::: "memory")
; #define PG8_BAR __builtin_amdgcn_s_barrier()
; #define PG8_SCHED __builtin_amdgcn_sched_barrier(0)
; template <class Epi, class Sched, bool ALIGN_EPI = false, bool SP2 = false, bool F8 = false>
; __device__ __forceinline__ void gemm_phase(PG8_LAS unsigned char* lds, const Gemm g, const Sched& S, const Epi& E, int wv) {
;     ...
;             PG8_LDB(B0, 1, 0); PG8_LDB(B1, 1, 1); PG8_SCHED; PG8_LDA(At, 1, 0); PG8_STAGE(PG8_SA(0, 1), a2 + hstepA, voffA);
;             PG8_WAIT_V(8); PG8_WAIT_L(0); PG8_BAR; PG8_MMA(0, 0, At, B0); PG8_MMA(0, 1, At, B1); PG8_BAR; PG8_SCHED;
;             PG8_LDA(At, 1, 1); PG8_STAGE(PG8_SB(1, 0), b3, voffB); PG8_STAGE(PG8_SB(1, 1), b3 + hstepB, voffB); PG8_STAGE(PG8_SA(1, 0), a3, voffA);
;             PG8_WAIT_V(8); PG8_WAIT_L(0); PG8_BAR; PG8_MMA(1, 0, At, B0); PG8_MMA(1, 1, At, B1); PG8_BAR; PG8_SCHED;
	v_add_u32_e32 v0, s59, v189
	v_add_u32_e32 v4, s60, v189
	ds_read_b128 v[24:27], v0
	ds_read_b128 v[28:31], v0 offset:1024
	ds_read_b128 v[16:19], v0 offset:2048
	ds_read_b128 v[20:23], v0 offset:3072
	ds_read_b128 v[8:11], v4
	ds_read_b128 v[12:15], v4 offset:1024
	ds_read_b128 v[0:3], v4 offset:2048
	ds_read_b128 v[4:7], v4 offset:3072
	s_add_u32 s24, s24, 0x40000
	s_addc_u32 s25, s25, 0
	s_mov_b32 m0, s42
	v_lshl_add_u64 v[200:201], s[24:25], 0, v[170:171]
	ds_read_b128 v[192:195], v191 offset:32768
	ds_read_b128 v[196:199], v191 offset:33792
	ds_read_b128 v[214:217], v191 offset:34816
	ds_read_b128 v[218:221], v191 offset:35840
	ds_read_b128 v[222:225], v191 offset:36864
	ds_read_b128 v[226:229], v191 offset:37888
	ds_read_b128 v[230:233], v191 offset:38912
	ds_read_b128 v[234:237], v191 offset:39936
	global_load_lds_dwordx4 v[200:201], off
	v_lshl_add_u64 v[200:201], s[24:25], 0, v[166:167]
	s_mov_b32 m0, s43
	s_nop 0
	global_load_lds_dwordx4 v[200:201], off
	s_waitcnt vmcnt(8)
	s_waitcnt lgkmcnt(0)
	s_barrier
	s_waitcnt lgkmcnt(0)
	v_mfma_f32_16x16x128_f8f6f4 v[160:163], v[24:31], v[192:199], v[160:163]
	v_mfma_f32_16x16x128_f8f6f4 v[156:159], v[16:23], v[192:199], v[156:159]
	v_mfma_f32_16x16x128_f8f6f4 v[144:147], v[24:31], v[214:221], v[144:147]
	v_mfma_f32_16x16x128_f8f6f4 v[140:143], v[16:23], v[214:221], v[140:143]
	v_mfma_f32_16x16x128_f8f6f4 v[124:127], v[24:31], v[222:229], v[124:127]
	v_mfma_f32_16x16x128_f8f6f4 v[120:123], v[16:23], v[222:229], v[120:123]
	v_mfma_f32_16x16x128_f8f6f4 v[108:111], v[24:31], v[230:237], v[108:111]
	v_mfma_f32_16x16x128_f8f6f4 v[104:107], v[16:23], v[230:237], v[104:107]
	v_mfma_f32_16x16x128_f8f6f4 v[152:155], v[8:15], v[192:199], v[152:155]
	v_mfma_f32_16x16x128_f8f6f4 v[148:151], v[0:7], v[192:199], v[148:151]
	v_mfma_f32_16x16x128_f8f6f4 v[136:139], v[8:15], v[214:221], v[136:139]
	v_mfma_f32_16x16x128_f8f6f4 v[132:135], v[0:7], v[214:221], v[132:135]
	v_mfma_f32_16x16x128_f8f6f4 v[116:119], v[8:15], v[222:229], v[116:119]
	v_mfma_f32_16x16x128_f8f6f4 v[112:115], v[0:7], v[222:229], v[112:115]
	v_mfma_f32_16x16x128_f8f6f4 v[100:103], v[8:15], v[230:237], v[100:103]
	v_mfma_f32_16x16x128_f8f6f4 v[96:99], v[0:7], v[230:237], v[96:99]
	s_barrier
	s_mov_b32 m0, s46
	v_lshl_add_u64 v[130:131], v[130:131], 0, s[52:53]
	s_add_u32 s22, s22, 0x40080
	ds_read_b128 v[192:195], v191 offset:49152
	ds_read_b128 v[196:199], v191 offset:50176
	ds_read_b128 v[214:217], v191 offset:51200
	ds_read_b128 v[218:221], v191 offset:52224
	ds_read_b128 v[222:225], v191 offset:53248
	ds_read_b128 v[226:229], v191 offset:54272
	ds_read_b128 v[230:233], v191 offset:55296
	ds_read_b128 v[234:237], v191 offset:56320
	global_load_lds_dwordx4 v[130:131], off
	v_lshl_add_u64 v[130:131], v[180:181], 0, s[52:53]
	s_mov_b32 m0, s47
	s_addc_u32 s23, s23, 0
	global_load_lds_dwordx4 v[130:131], off
	v_lshl_add_u64 v[130:131], s[22:23], 0, v[168:169]
	s_mov_b32 m0, s54
	s_nop 0
	global_load_lds_dwordx4 v[130:131], off
	v_lshl_add_u64 v[130:131], s[22:23], 0, v[164:165]
	s_mov_b32 m0, s55
	s_nop 0
	global_load_lds_dwordx4 v[130:131], off
	v_lshl_add_u64 v[130:131], v[182:183], 0, s[52:53]
	s_mov_b32 m0, s48
	s_nop 0
	global_load_lds_dwordx4 v[130:131], off
	v_lshl_add_u64 v[130:131], v[184:185], 0, s[52:53]
	s_mov_b32 m0, s49
	s_nop 0
	global_load_lds_dwordx4 v[130:131], off
	s_waitcnt vmcnt(8)
	s_waitcnt lgkmcnt(0)
	s_barrier
	s_waitcnt lgkmcnt(0)
	v_mfma_f32_16x16x128_f8f6f4 v[92:95], v[24:31], v[192:199], v[92:95]
	v_mfma_f32_16x16x128_f8f6f4 v[88:91], v[16:23], v[192:199], v[88:91]
	v_mfma_f32_16x16x128_f8f6f4 v[76:79], v[24:31], v[214:221], v[76:79]
	v_mfma_f32_16x16x128_f8f6f4 v[72:75], v[16:23], v[214:221], v[72:75]
	v_mfma_f32_16x16x128_f8f6f4 v[60:63], v[24:31], v[222:229], v[60:63]
	v_mfma_f32_16x16x128_f8f6f4 v[56:59], v[16:23], v[222:229], v[56:59]
	v_mfma_f32_16x16x128_f8f6f4 v[44:47], v[24:31], v[230:237], v[44:47]
	v_mfma_f32_16x16x128_f8f6f4 v[40:43], v[16:23], v[230:237], v[40:43]
	v_mfma_f32_16x16x128_f8f6f4 v[84:87], v[8:15], v[192:199], v[84:87]
	v_mfma_f32_16x16x128_f8f6f4 v[80:83], v[0:7], v[192:199], v[80:83]
	v_mfma_f32_16x16x128_f8f6f4 v[68:71], v[8:15], v[214:221], v[68:71]
	v_mfma_f32_16x16x128_f8f6f4 v[64:67], v[0:7], v[214:221], v[64:67]
	v_mfma_f32_16x16x128_f8f6f4 v[52:55], v[8:15], v[222:229], v[52:55]
	v_mfma_f32_16x16x128_f8f6f4 v[48:51], v[0:7], v[222:229], v[48:51]
	v_mfma_f32_16x16x128_f8f6f4 v[36:39], v[8:15], v[230:237], v[36:39]
	v_mfma_f32_16x16x128_f8f6f4 v[32:35], v[0:7], v[230:237], v[32:35]
	s_barrier
	s_add_i32 s73, s73, 2
	s_add_u32 s20, s20, 0x100
	s_addc_u32 s21, s21, 0
	s_cmp_gt_u32 s73, 13
	s_cbranch_scc1 .LBB0_641

; #define PG8_STAGE(bufoff, gbase, voff) do { _Pragma("unroll") for (int _i = 0; _i < 2; ++_i) \
;         __builtin_amdgcn_global_load_lds((const unsigned*)((const char*)(gbase) + (voff)[_i]), (PG8_LAS unsigned*)(lds + (bufoff) + ldsw + _i * 8192), 16, 0, 0); } while (0)
; #define PG8_LDA(dst, b, h) do { _Pragma("unroll") for (int m = 0; m < 4; ++m) _Pragma("unroll") for (int k = 0; k < 2; ++k) dst[m][k] = *(const PG8_LAS bf16x8*)(lds + PG8_SA(b, h) + aoff + m * 2048 + k * 1024); } while (0)
; #define PG8_LDB(dst, b, h) do { _Pragma("unroll") for (int n = 0; n < 2; ++n) _Pragma("unroll") for (int k = 0; k < 2; ++k) dst[n][k] = *(const PG8_LAS bf16x8*)(lds + (SP2 ? PG8_SB(b, hw) + (h) * 4096 : PG8_SB(b, h)) + boff + n * 2048 + k * 1024); } while (0)
; #define PG8_WAIT_V(n) asm volatile("s_waitcnt vmcnt(" #n ")" ::: "memory")
; #define PG8_WAIT_L(n) asm volatile("s_waitcnt lgkmcnt(" #n ")" ::: "memory")
; #define PG8_BAR __builtin_amdgcn_s_barrier()
; #define PG8_SCHED __builtin_amdgcn_sched_barrier(0)
; template <class Epi, class Sched, bool ALIGN_EPI = false, bool SP2 = false, bool F8 = false>
; __device__ __forceinline__ void gemm_phase(PG8_LAS unsigned char* lds, const Gemm g, const Sched& S, const Epi& E, int wv) {
;     ...
;             const char* a1 = cA + (size_t)(t + 1) * kstep;
;             const char* a2 = last ? nA : cA + (size_t)(t + 2) * kstep; const char* b2 = last ? nB : cB + (size_t)(t + 2) * kstep;
;             const char* a3 = a2 + kstep; const char* b3 = b2 + kstep;
;             if (last && has_next) S.a_ready(nxt);
;             if constexpr (SP2) {
;             PG8_LDB(B0, 0, 0); PG8_LDB(B1, 0, 1); PG8_SCHED; PG8_LDA(At, 0, 0); PG8_STAGE(PG8_SA(1, 1), a1 + hstepA, voffA);
;             PG8_WAIT_V(8); PG8_WAIT_L(0); PG8_BAR; PG8_MMA(0, 0, At, B0); PG8_MMA(0, 1, At, B1); PG8_BAR; PG8_SCHED;
;             PG8_LDA(At, 0, 1); PG8_STAGE(PG8_SB(0, 0), b2, voffB); PG8_STAGE(PG8_SB(0, 1), b2 + hstepB, voffB); PG8_STAGE(PG8_SA(0, 0), a2, voffA);
;             PG8_WAIT_V(8); PG8_WAIT_L(0); PG8_BAR; PG8_MMA(1, 0, At, B0); PG8_MMA(1, 1, At, B1); PG8_BAR; PG8_SCHED;
.LBB0_711:
	v_add_u32_e32 v0, s48, v181
	v_add_u32_e32 v4, s49, v181
	ds_read_b128 v[24:27], v0
	ds_read_b128 v[28:31], v0 offset:1024
	ds_read_b128 v[16:19], v0 offset:2048
	ds_read_b128 v[20:23], v0 offset:3072
	ds_read_b128 v[8:11], v4
	ds_read_b128 v[12:15], v4 offset:1024
	ds_read_b128 v[0:3], v4 offset:2048
	ds_read_b128 v[4:7], v4 offset:3072
	s_add_u32 s20, s18, 0xfffc0080
	s_addc_u32 s21, s19, -1
	s_cmp_eq_u32 s61, 12
	s_cselect_b32 s23, s9, s21
	s_cselect_b32 s22, s15, s20
	s_cselect_b32 s21, s7, s60
	s_cselect_b32 s20, s58, s59
	v_lshl_add_u64 v[200:201], s[18:19], 0, v[168:169]
	s_add_i32 m0, s17, 0xc000
	ds_read_b128 v[172:175], v183
	ds_read_b128 v[176:179], v183 offset:1024
	ds_read_b128 v[184:187], v183 offset:2048
	ds_read_b128 v[188:191], v183 offset:3072
	ds_read_b128 v[192:195], v183 offset:4096
	ds_read_b128 v[196:199], v183 offset:5120
	ds_read_b128 v[214:217], v183 offset:6144
	ds_read_b128 v[218:221], v183 offset:7168
	global_load_lds_dwordx4 v[200:201], off
	v_lshl_add_u64 v[200:201], s[18:19], 0, v[170:171]
	s_add_i32 m0, s17, 0xe000
	s_nop 0
	global_load_lds_dwordx4 v[200:201], off
	s_waitcnt vmcnt(8)
	s_waitcnt lgkmcnt(0)
	s_barrier
	s_waitcnt lgkmcnt(0)
	v_mfma_f32_16x16x128_f8f6f4 v[158:161], v[24:31], v[172:179], v[158:161]
	v_mfma_f32_16x16x128_f8f6f4 v[154:157], v[16:23], v[172:179], v[154:157]
	v_mfma_f32_16x16x128_f8f6f4 v[146:149], v[24:31], v[184:191], v[146:149]
	v_mfma_f32_16x16x128_f8f6f4 v[138:141], v[16:23], v[184:191], v[138:141]
	v_mfma_f32_16x16x128_f8f6f4 v[130:133], v[24:31], v[192:199], v[130:133]
	v_mfma_f32_16x16x128_f8f6f4 v[120:123], v[16:23], v[192:199], v[120:123]
	v_mfma_f32_16x16x128_f8f6f4 v[112:115], v[24:31], v[214:221], v[112:115]
	v_mfma_f32_16x16x128_f8f6f4 v[104:107], v[16:23], v[214:221], v[104:107]
	v_mfma_f32_16x16x128_f8f6f4 v[150:153], v[8:15], v[172:179], v[150:153]
	v_mfma_f32_16x16x128_f8f6f4 v[142:145], v[0:7], v[172:179], v[142:145]
	v_mfma_f32_16x16x128_f8f6f4 v[134:137], v[8:15], v[184:191], v[134:137]
	v_mfma_f32_16x16x128_f8f6f4 v[124:127], v[0:7], v[184:191], v[124:127]
	v_mfma_f32_16x16x128_f8f6f4 v[116:119], v[8:15], v[192:199], v[116:119]
	v_mfma_f32_16x16x128_f8f6f4 v[108:111], v[0:7], v[192:199], v[108:111]
	v_mfma_f32_16x16x128_f8f6f4 v[100:103], v[8:15], v[214:221], v[100:103]
	v_mfma_f32_16x16x128_f8f6f4 v[96:99], v[0:7], v[214:221], v[96:99]
	s_barrier
	s_mov_b32 m0, s30
	v_lshl_add_u64 v[172:173], s[20:21], 0, v[128:129]
	s_add_u32 s62, s20, 0x40000
	ds_read_b128 v[184:187], v183 offset:16384
	ds_read_b128 v[188:191], v183 offset:17408
	ds_read_b128 v[192:195], v183 offset:18432
	ds_read_b128 v[196:199], v183 offset:19456
	ds_read_b128 v[214:217], v183 offset:20480
	ds_read_b128 v[218:221], v183 offset:21504
	ds_read_b128 v[222:225], v183 offset:22528
	ds_read_b128 v[226:229], v183 offset:23552
	global_load_lds_dwordx4 v[172:173], off
	v_lshl_add_u64 v[174:175], s[20:21], 0, v[162:163]
	s_mov_b32 m0, s31
	s_addc_u32 s63, s21, 0
	global_load_lds_dwordx4 v[174:175], off
	v_lshl_add_u64 v[176:177], s[62:63], 0, v[128:129]
	s_mov_b32 m0, s34
	v_lshl_add_u64 v[178:179], s[22:23], 0, v[164:165]
	global_load_lds_dwordx4 v[176:177], off
	v_lshl_add_u64 v[176:177], s[62:63], 0, v[162:163]
	s_mov_b32 m0, s35
	s_nop 0
	global_load_lds_dwordx4 v[176:177], off
	v_lshl_add_u64 v[176:177], s[22:23], 0, v[166:167]
	s_mov_b32 m0, s17
	s_nop 0
	global_load_lds_dwordx4 v[176:177], off
	s_mov_b32 m0, s38
	s_nop 0
	global_load_lds_dwordx4 v[178:179], off
	s_waitcnt vmcnt(8)
	s_waitcnt lgkmcnt(0)
	s_barrier
	s_waitcnt lgkmcnt(0)
	v_mfma_f32_16x16x128_f8f6f4 v[92:95], v[24:31], v[184:191], v[92:95]
	v_mfma_f32_16x16x128_f8f6f4 v[88:91], v[16:23], v[184:191], v[88:91]
	v_mfma_f32_16x16x128_f8f6f4 v[80:83], v[24:31], v[192:199], v[80:83]
	v_mfma_f32_16x16x128_f8f6f4 v[72:75], v[16:23], v[192:199], v[72:75]
	v_mfma_f32_16x16x128_f8f6f4 v[64:67], v[24:31], v[214:221], v[64:67]
	v_mfma_f32_16x16x128_f8f6f4 v[56:59], v[16:23], v[214:221], v[56:59]
	v_mfma_f32_16x16x128_f8f6f4 v[48:51], v[24:31], v[222:229], v[48:51]
	v_mfma_f32_16x16x128_f8f6f4 v[40:43], v[16:23], v[222:229], v[40:43]
	v_mfma_f32_16x16x128_f8f6f4 v[84:87], v[8:15], v[184:191], v[84:87]
	v_mfma_f32_16x16x128_f8f6f4 v[76:79], v[0:7], v[184:191], v[76:79]
	v_mfma_f32_16x16x128_f8f6f4 v[68:71], v[8:15], v[192:199], v[68:71]
	v_mfma_f32_16x16x128_f8f6f4 v[60:63], v[0:7], v[192:199], v[60:63]
	v_mfma_f32_16x16x128_f8f6f4 v[52:55], v[8:15], v[214:221], v[52:55]
	v_mfma_f32_16x16x128_f8f6f4 v[44:47], v[0:7], v[214:221], v[44:47]
	v_mfma_f32_16x16x128_f8f6f4 v[36:39], v[8:15], v[222:229], v[36:39]
	v_mfma_f32_16x16x128_f8f6f4 v[32:35], v[0:7], v[222:229], v[32:35]
	s_barrier
; #define PG8_STAGE(bufoff, gbase, voff) do { _Pragma("unroll") for (int _i = 0; _i < 2; ++_i) \
;         __builtin_amdgcn_global_load_lds((const unsigned*)((const char*)(gbase) + (voff)[_i]), (PG8_LAS unsigned*)(lds + (bufoff) + ldsw + _i * 8192), 16, 0, 0); } while (0)
; #define PG8_LDA(dst, b, h) do { _Pragma("unroll") for (int m = 0; m < 4; ++m) _Pragma("unroll") for (int k = 0; k < 2; ++k) dst[m][k] = *(const PG8_LAS bf16x8*)(lds + PG8_SA(b, h) + aoff + m * 2048 + k * 1024); } while (0)
; #define PG8_LDB(dst, b, h) do { _Pragma("unroll") for (int n = 0; n < 2; ++n) _Pragma("unroll") for (int k = 0; k < 2; ++k) dst[n][k] = *(const PG8_LAS bf16x8*)(lds + (SP2 ? PG8_SB(b, hw) + (h) * 4096 : PG8_SB(b, h)) + boff + n * 2048 + k * 1024); } while (0)
; #define PG8_WAIT_V(n) asm volatile("s_waitcnt vmcnt(" #n ")" ::: "memory")
; #define PG8_WAIT_L(n) asm volatile("s_waitcnt lgkmcnt(" #n ")" ::: "memory")
; #define PG8_BAR __builtin_amdgcn_s_barrier()
; #define PG8_SCHED __builtin_amdgcn_sched_barrier(0)
; template <class Epi, class Sched, bool ALIGN_EPI = false, bool SP2 = false, bool F8 = false>
; __device__ __forceinline__ void gemm_phase(PG8_LAS unsigned char* lds, const Gemm g, const Sched& S, const Epi& E, int wv) {
;     ...
;             PG8_LDB(B0, 1, 0); PG8_LDB(B1, 1, 1); PG8_SCHED; PG8_LDA(At, 1, 0); PG8_STAGE(PG8_SA(0, 1), a2 + hstepA, voffA);
;             PG8_WAIT_V(8); PG8_WAIT_L(0); PG8_BAR; PG8_MMA(0, 0, At, B0); PG8_MMA(0, 1, At, B1); PG8_BAR; PG8_SCHED;
;             PG8_LDA(At, 1, 1); PG8_STAGE(PG8_SB(1, 0), b3, voffB); PG8_STAGE(PG8_SB(1, 1), b3 + hstepB, voffB); PG8_STAGE(PG8_SA(1, 0), a3, voffA);
;             PG8_WAIT_V(8); PG8_WAIT_L(0); PG8_BAR; PG8_MMA(1, 0, At, B0); PG8_MMA(1, 1, At, B1); PG8_BAR; PG8_SCHED;
;     ...
;         if constexpr (F8) asm volatile("s_nop 15\n\ts_nop 15" ::: "memory");
	v_add_u32_e32 v12, s54, v181
	v_add_u32_e32 v28, s55, v181
	ds_read_b128 v[0:3], v12
	ds_read_b128 v[4:7], v12 offset:1024
	ds_read_b128 v[8:11], v12 offset:2048
	ds_read_b128 v[12:15], v12 offset:3072
	ds_read_b128 v[16:19], v28
	ds_read_b128 v[20:23], v28 offset:1024
	ds_read_b128 v[24:27], v28 offset:2048
	ds_read_b128 v[28:31], v28 offset:3072
	s_add_u32 s22, s22, 0x40000
	s_addc_u32 s23, s23, 0
	s_mov_b32 m0, s39
	v_lshl_add_u64 v[200:201], s[22:23], 0, v[166:167]
	ds_read_b128 v[184:187], v183 offset:32768
	ds_read_b128 v[188:191], v183 offset:33792
	ds_read_b128 v[192:195], v183 offset:34816
	ds_read_b128 v[196:199], v183 offset:35840
	ds_read_b128 v[214:217], v183 offset:36864
	ds_read_b128 v[218:221], v183 offset:37888
	ds_read_b128 v[222:225], v183 offset:38912
	ds_read_b128 v[226:229], v183 offset:39936
	global_load_lds_dwordx4 v[200:201], off
	v_lshl_add_u64 v[200:201], s[22:23], 0, v[164:165]
	s_mov_b32 m0, s40
	s_nop 0
	global_load_lds_dwordx4 v[200:201], off
	s_waitcnt vmcnt(8)
	s_waitcnt lgkmcnt(0)
	s_barrier
	s_waitcnt lgkmcnt(0)
	v_mfma_f32_16x16x128_f8f6f4 v[158:161], v[0:7], v[184:191], v[158:161]
	v_mfma_f32_16x16x128_f8f6f4 v[154:157], v[8:15], v[184:191], v[154:157]
	v_mfma_f32_16x16x128_f8f6f4 v[146:149], v[0:7], v[192:199], v[146:149]
	v_mfma_f32_16x16x128_f8f6f4 v[138:141], v[8:15], v[192:199], v[138:141]
	v_mfma_f32_16x16x128_f8f6f4 v[130:133], v[0:7], v[214:221], v[130:133]
	v_mfma_f32_16x16x128_f8f6f4 v[120:123], v[8:15], v[214:221], v[120:123]
	v_mfma_f32_16x16x128_f8f6f4 v[112:115], v[0:7], v[222:229], v[112:115]
	v_mfma_f32_16x16x128_f8f6f4 v[104:107], v[8:15], v[222:229], v[104:107]
	v_mfma_f32_16x16x128_f8f6f4 v[150:153], v[16:23], v[184:191], v[150:153]
	v_mfma_f32_16x16x128_f8f6f4 v[142:145], v[24:31], v[184:191], v[142:145]
	v_mfma_f32_16x16x128_f8f6f4 v[134:137], v[16:23], v[192:199], v[134:137]
	v_mfma_f32_16x16x128_f8f6f4 v[124:127], v[24:31], v[192:199], v[124:127]
	v_mfma_f32_16x16x128_f8f6f4 v[116:119], v[16:23], v[214:221], v[116:119]
	v_mfma_f32_16x16x128_f8f6f4 v[108:111], v[24:31], v[214:221], v[108:111]
	v_mfma_f32_16x16x128_f8f6f4 v[100:103], v[16:23], v[222:229], v[100:103]
	v_mfma_f32_16x16x128_f8f6f4 v[96:99], v[24:31], v[222:229], v[96:99]
	s_barrier
	s_mov_b32 m0, s42
	v_lshl_add_u64 v[172:173], v[172:173], 0, s[52:53]
	s_add_u32 s20, s20, 0x40080
	ds_read_b128 v[184:187], v183 offset:49152
	ds_read_b128 v[188:191], v183 offset:50176
	ds_read_b128 v[192:195], v183 offset:51200
	ds_read_b128 v[196:199], v183 offset:52224
	ds_read_b128 v[214:217], v183 offset:53248
	ds_read_b128 v[218:221], v183 offset:54272
	ds_read_b128 v[222:225], v183 offset:55296
	ds_read_b128 v[226:229], v183 offset:56320
	global_load_lds_dwordx4 v[172:173], off
	v_lshl_add_u64 v[172:173], v[174:175], 0, s[52:53]
	s_mov_b32 m0, s43
	s_addc_u32 s21, s21, 0
	global_load_lds_dwordx4 v[172:173], off
	v_lshl_add_u64 v[172:173], s[20:21], 0, v[128:129]
	s_mov_b32 m0, s46
	s_nop 0
	global_load_lds_dwordx4 v[172:173], off
	v_lshl_add_u64 v[172:173], s[20:21], 0, v[162:163]
	s_mov_b32 m0, s47
	s_nop 0
	global_load_lds_dwordx4 v[172:173], off
	v_lshl_add_u64 v[172:173], v[176:177], 0, s[52:53]
	s_mov_b32 m0, s44
	s_nop 0
	global_load_lds_dwordx4 v[172:173], off
	v_lshl_add_u64 v[172:173], v[178:179], 0, s[52:53]
	s_mov_b32 m0, s45
	s_nop 0
	global_load_lds_dwordx4 v[172:173], off
	s_waitcnt vmcnt(8)
	s_waitcnt lgkmcnt(0)
	s_barrier
	s_waitcnt lgkmcnt(0)
	v_mfma_f32_16x16x128_f8f6f4 v[92:95], v[0:7], v[184:191], v[92:95]
	v_mfma_f32_16x16x128_f8f6f4 v[88:91], v[8:15], v[184:191], v[88:91]
	v_mfma_f32_16x16x128_f8f6f4 v[80:83], v[0:7], v[192:199], v[80:83]
	v_mfma_f32_16x16x128_f8f6f4 v[72:75], v[8:15], v[192:199], v[72:75]
	v_mfma_f32_16x16x128_f8f6f4 v[64:67], v[0:7], v[214:221], v[64:67]
	v_mfma_f32_16x16x128_f8f6f4 v[56:59], v[8:15], v[214:221], v[56:59]
	v_mfma_f32_16x16x128_f8f6f4 v[48:51], v[0:7], v[222:229], v[48:51]
	v_mfma_f32_16x16x128_f8f6f4 v[40:43], v[8:15], v[222:229], v[40:43]
	v_mfma_f32_16x16x128_f8f6f4 v[84:87], v[16:23], v[184:191], v[84:87]
	v_mfma_f32_16x16x128_f8f6f4 v[76:79], v[24:31], v[184:191], v[76:79]
	v_mfma_f32_16x16x128_f8f6f4 v[68:71], v[16:23], v[192:199], v[68:71]
	v_mfma_f32_16x16x128_f8f6f4 v[60:63], v[24:31], v[192:199], v[60:63]
	v_mfma_f32_16x16x128_f8f6f4 v[52:55], v[16:23], v[214:221], v[52:55]
	v_mfma_f32_16x16x128_f8f6f4 v[44:47], v[24:31], v[214:221], v[44:47]
	v_mfma_f32_16x16x128_f8f6f4 v[36:39], v[16:23], v[222:229], v[36:39]
	v_mfma_f32_16x16x128_f8f6f4 v[32:35], v[24:31], v[222:229], v[32:35]
	s_barrier
	s_add_i32 s61, s61, 2
	s_add_u32 s18, s18, 0x100
	s_addc_u32 s19, s19, 0
	s_add_u32 s59, s59, 0x100
	s_addc_u32 s60, s60, 0
	s_cmp_gt_u32 s61, 13
	s_cbranch_scc0 .LBB0_711
	s_nop 15
	s_nop 15
	s_and_b64 vcc, exec, s[4:5]
	s_cbranch_vccz .LBB0_714
	s_barrier

; #define PG8_STAGE(bufoff, gbase, voff) do { _Pragma("unroll") for (int _i = 0; _i < 2; ++_i) \
;         __builtin_amdgcn_global_load_lds((const unsigned*)((const char*)(gbase) + (voff)[_i]), (PG8_LAS unsigned*)(lds + (bufoff) + ldsw + _i * 8192), 16, 0, 0); } while (0)
; #define PG8_LDA(dst, b, h) do { _Pragma("unroll") for (int m = 0; m < 4; ++m) _Pragma("unroll") for (int k = 0; k < 2; ++k) dst[m][k] = *(const PG8_LAS bf16x8*)(lds + PG8_SA(b, h) + aoff + m * 2048 + k * 1024); } while (0)
; #define PG8_LDB(dst, b, h) do { _Pragma("unroll") for (int n = 0; n < 2; ++n) _Pragma("unroll") for (int k = 0; k < 2; ++k) dst[n][k] = *(const PG8_LAS bf16x8*)(lds + (SP2 ? PG8_SB(b, hw) + (h) * 4096 : PG8_SB(b, h)) + boff + n * 2048 + k * 1024); } while (0)
; #define PG8_WAIT_V(n) asm volatile("s_waitcnt vmcnt(" #n ")" ::: "memory")
; #define PG8_WAIT_L(n) asm volatile("s_waitcnt lgkmcnt(" #n ")" ::: "memory")
; #define PG8_BAR __builtin_amdgcn_s_barrier()
; #define PG8_SCHED __builtin_amdgcn_sched_barrier(0)
; template <class Epi, class Sched, bool ALIGN_EPI = false, bool SP2 = false, bool F8 = false>
; __device__ __forceinline__ void gemm_phase(PG8_LAS unsigned char* lds, const Gemm g, const Sched& S, const Epi& E, int wv) {
;     ...
;             const char* a1 = cA + (size_t)(t + 1) * kstep;
;             const char* a2 = last ? nA : cA + (size_t)(t + 2) * kstep; const char* b2 = last ? nB : cB + (size_t)(t + 2) * kstep;
;             const char* a3 = a2 + kstep; const char* b3 = b2 + kstep;
;             if (last && has_next) S.a_ready(nxt);
;             if constexpr (SP2) {
;             PG8_LDB(B0, 0, 0); PG8_LDB(B1, 0, 1); PG8_SCHED; PG8_LDA(At, 0, 0); PG8_STAGE(PG8_SA(1, 1), a1 + hstepA, voffA);
;             PG8_WAIT_V(8); PG8_WAIT_L(0); PG8_BAR; PG8_MMA(0, 0, At, B0); PG8_MMA(0, 1, At, B1); PG8_BAR; PG8_SCHED;
;             PG8_LDA(At, 0, 1); PG8_STAGE(PG8_SB(0, 0), b2, voffB); PG8_STAGE(PG8_SB(0, 1), b2 + hstepB, voffB); PG8_STAGE(PG8_SA(0, 0), a2, voffA);
;             PG8_WAIT_V(8); PG8_WAIT_L(0); PG8_BAR; PG8_MMA(1, 0, At, B0); PG8_MMA(1, 1, At, B1); PG8_BAR; PG8_SCHED;
.LBB0_846:
	v_add_u32_e32 v140, s47, v143
	ds_read_b128 v[146:149], v140
	ds_read_b128 v[150:153], v140 offset:1024
	ds_read_b128 v[154:157], v140 offset:2048
	ds_read_b128 v[158:161], v140 offset:3072
	v_add_u32_e32 v140, s48, v143
	ds_read_b128 v[162:165], v140
	ds_read_b128 v[166:169], v140 offset:1024
	ds_read_b128 v[170:173], v140 offset:2048
	ds_read_b128 v[174:177], v140 offset:3072
	s_add_u32 s22, s20, 0xfff80080
	s_addc_u32 s23, s21, -1
	s_cmp_eq_u32 s61, 28
	s_cselect_b32 s25, s11, s23
	s_cselect_b32 s24, s57, s22
	s_cselect_b32 s23, s9, s60
	s_cselect_b32 s22, s58, s59
	v_lshl_add_u64 v[140:141], s[20:21], 0, v[136:137]
	s_add_i32 m0, s13, 0xc000
	ds_read_b128 v[178:181], v145
	ds_read_b128 v[182:185], v145 offset:1024
	ds_read_b128 v[186:189], v145 offset:2048
	ds_read_b128 v[190:193], v145 offset:3072
	ds_read_b128 v[194:197], v145 offset:4096
	ds_read_b128 v[198:201], v145 offset:5120
	ds_read_b128 v[202:205], v145 offset:6144
	ds_read_b128 v[208:211], v145 offset:7168
	global_load_lds_dwordx4 v[140:141], off
	v_lshl_add_u64 v[140:141], s[20:21], 0, v[138:139]
	s_add_i32 m0, s13, 0xe000
	s_nop 0
	global_load_lds_dwordx4 v[140:141], off
	s_waitcnt vmcnt(8)
	s_waitcnt lgkmcnt(0)
	s_barrier
	s_waitcnt lgkmcnt(0)
	v_mfma_f32_16x16x32_bf16 v[124:127], v[146:149], v[178:181], v[124:127]
	v_mfma_f32_16x16x32_bf16 v[120:123], v[154:157], v[178:181], v[120:123]
	v_mfma_f32_16x16x32_bf16 v[116:119], v[146:149], v[186:189], v[116:119]
	v_mfma_f32_16x16x32_bf16 v[108:111], v[154:157], v[186:189], v[108:111]
	v_mfma_f32_16x16x32_bf16 v[100:103], v[146:149], v[194:197], v[100:103]
	v_mfma_f32_16x16x32_bf16 v[92:95], v[154:157], v[194:197], v[92:95]
	v_mfma_f32_16x16x32_bf16 v[84:87], v[146:149], v[202:205], v[84:87]
	v_mfma_f32_16x16x32_bf16 v[76:79], v[154:157], v[202:205], v[76:79]
	v_mfma_f32_16x16x32_bf16 v[124:127], v[150:153], v[182:185], v[124:127]
	v_mfma_f32_16x16x32_bf16 v[120:123], v[158:161], v[182:185], v[120:123]
	v_mfma_f32_16x16x32_bf16 v[116:119], v[150:153], v[190:193], v[116:119]
	v_mfma_f32_16x16x32_bf16 v[108:111], v[158:161], v[190:193], v[108:111]
	v_mfma_f32_16x16x32_bf16 v[100:103], v[150:153], v[198:201], v[100:103]
	v_mfma_f32_16x16x32_bf16 v[92:95], v[158:161], v[198:201], v[92:95]
	v_mfma_f32_16x16x32_bf16 v[84:87], v[150:153], v[208:211], v[84:87]
	v_mfma_f32_16x16x32_bf16 v[76:79], v[158:161], v[208:211], v[76:79]
	v_mfma_f32_16x16x32_bf16 v[112:115], v[162:165], v[178:181], v[112:115]
	v_mfma_f32_16x16x32_bf16 v[104:107], v[170:173], v[178:181], v[104:107]
	v_mfma_f32_16x16x32_bf16 v[96:99], v[162:165], v[186:189], v[96:99]
	v_mfma_f32_16x16x32_bf16 v[88:91], v[170:173], v[186:189], v[88:91]
	v_mfma_f32_16x16x32_bf16 v[80:83], v[162:165], v[194:197], v[80:83]
	v_mfma_f32_16x16x32_bf16 v[72:75], v[170:173], v[194:197], v[72:75]
	v_mfma_f32_16x16x32_bf16 v[68:71], v[162:165], v[202:205], v[68:71]
	v_mfma_f32_16x16x32_bf16 v[64:67], v[170:173], v[202:205], v[64:67]
	v_mfma_f32_16x16x32_bf16 v[112:115], v[166:169], v[182:185], v[112:115]
	v_mfma_f32_16x16x32_bf16 v[104:107], v[174:177], v[182:185], v[104:107]
	v_mfma_f32_16x16x32_bf16 v[96:99], v[166:169], v[190:193], v[96:99]
	v_mfma_f32_16x16x32_bf16 v[88:91], v[174:177], v[190:193], v[88:91]
	v_mfma_f32_16x16x32_bf16 v[80:83], v[166:169], v[198:201], v[80:83]
	v_mfma_f32_16x16x32_bf16 v[72:75], v[174:177], v[198:201], v[72:75]
	v_mfma_f32_16x16x32_bf16 v[68:71], v[166:169], v[208:211], v[68:71]
	v_mfma_f32_16x16x32_bf16 v[64:67], v[174:177], v[208:211], v[64:67]
	s_barrier
	s_mov_b32 m0, s15
	v_lshl_add_u64 v[140:141], s[22:23], 0, v[128:129]
	s_add_u32 s62, s22, 0x80000
	ds_read_b128 v[178:181], v145 offset:16384
	ds_read_b128 v[182:185], v145 offset:17408
	ds_read_b128 v[186:189], v145 offset:18432
	ds_read_b128 v[190:193], v145 offset:19456
	ds_read_b128 v[194:197], v145 offset:20480
	ds_read_b128 v[198:201], v145 offset:21504
	ds_read_b128 v[202:205], v145 offset:22528
	ds_read_b128 v[208:211], v145 offset:23552
	global_load_lds_dwordx4 v[140:141], off
	v_lshl_add_u64 v[214:215], s[22:23], 0, v[130:131]
	s_mov_b32 m0, s34
	s_addc_u32 s63, s23, 0
	global_load_lds_dwordx4 v[214:215], off
	v_lshl_add_u64 v[216:217], s[62:63], 0, v[128:129]
	s_mov_b32 m0, s35
	v_lshl_add_u64 v[218:219], s[24:25], 0, v[132:133]
	global_load_lds_dwordx4 v[216:217], off
	v_lshl_add_u64 v[216:217], s[62:63], 0, v[130:131]
	s_mov_b32 m0, s36
	s_nop 0
	global_load_lds_dwordx4 v[216:217], off
	v_lshl_add_u64 v[216:217], s[24:25], 0, v[134:135]
	s_mov_b32 m0, s13
	s_nop 0
	global_load_lds_dwordx4 v[216:217], off
	s_mov_b32 m0, s37
	s_nop 0
	global_load_lds_dwordx4 v[218:219], off
	s_waitcnt vmcnt(8)
	s_waitcnt lgkmcnt(0)
	s_barrier
; #define PG8_STAGE(bufoff, gbase, voff) do { _Pragma("unroll") for (int _i = 0; _i < 2; ++_i) \
;         __builtin_amdgcn_global_load_lds((const unsigned*)((const char*)(gbase) + (voff)[_i]), (PG8_LAS unsigned*)(lds + (bufoff) + ldsw + _i * 8192), 16, 0, 0); } while (0)
; #define PG8_LDA(dst, b, h) do { _Pragma("unroll") for (int m = 0; m < 4; ++m) _Pragma("unroll") for (int k = 0; k < 2; ++k) dst[m][k] = *(const PG8_LAS bf16x8*)(lds + PG8_SA(b, h) + aoff + m * 2048 + k * 1024); } while (0)
; #define PG8_LDB(dst, b, h) do { _Pragma("unroll") for (int n = 0; n < 2; ++n) _Pragma("unroll") for (int k = 0; k < 2; ++k) dst[n][k] = *(const PG8_LAS bf16x8*)(lds + (SP2 ? PG8_SB(b, hw) + (h) * 4096 : PG8_SB(b, h)) + boff + n * 2048 + k * 1024); } while (0)
; #define PG8_WAIT_V(n) asm volatile("s_waitcnt vmcnt(" #n ")" ::: "memory")
; #define PG8_WAIT_L(n) asm volatile("s_waitcnt lgkmcnt(" #n ")" ::: "memory")
; #define PG8_BAR __builtin_amdgcn_s_barrier()
; #define PG8_SCHED __builtin_amdgcn_sched_barrier(0)
; template <class Epi, class Sched, bool ALIGN_EPI = false, bool SP2 = false, bool F8 = false>
; __device__ __forceinline__ void gemm_phase(PG8_LAS unsigned char* lds, const Gemm g, const Sched& S, const Epi& E, int wv) {
;     ...
;             PG8_WAIT_V(8); PG8_WAIT_L(0); PG8_BAR; PG8_MMA(1, 0, At, B0); PG8_MMA(1, 1, At, B1); PG8_BAR; PG8_SCHED;
;             PG8_LDB(B0, 1, 0); PG8_LDB(B1, 1, 1); PG8_SCHED; PG8_LDA(At, 1, 0); PG8_STAGE(PG8_SA(0, 1), a2 + hstepA, voffA);
;             PG8_WAIT_V(8); PG8_WAIT_L(0); PG8_BAR; PG8_MMA(0, 0, At, B0); PG8_MMA(0, 1, At, B1); PG8_BAR; PG8_SCHED;
	s_waitcnt lgkmcnt(0)
	v_mfma_f32_16x16x32_bf16 v[60:63], v[146:149], v[178:181], v[60:63]
	v_mfma_f32_16x16x32_bf16 v[56:59], v[154:157], v[178:181], v[56:59]
	v_mfma_f32_16x16x32_bf16 v[52:55], v[146:149], v[186:189], v[52:55]
	v_mfma_f32_16x16x32_bf16 v[44:47], v[154:157], v[186:189], v[44:47]
	v_mfma_f32_16x16x32_bf16 v[36:39], v[146:149], v[194:197], v[36:39]
	v_mfma_f32_16x16x32_bf16 v[28:31], v[154:157], v[194:197], v[28:31]
	v_mfma_f32_16x16x32_bf16 v[20:23], v[146:149], v[202:205], v[20:23]
	v_mfma_f32_16x16x32_bf16 v[12:15], v[154:157], v[202:205], v[12:15]
	v_mfma_f32_16x16x32_bf16 v[60:63], v[150:153], v[182:185], v[60:63]
	v_mfma_f32_16x16x32_bf16 v[56:59], v[158:161], v[182:185], v[56:59]
	v_mfma_f32_16x16x32_bf16 v[52:55], v[150:153], v[190:193], v[52:55]
	v_mfma_f32_16x16x32_bf16 v[44:47], v[158:161], v[190:193], v[44:47]
	v_mfma_f32_16x16x32_bf16 v[36:39], v[150:153], v[198:201], v[36:39]
	v_mfma_f32_16x16x32_bf16 v[28:31], v[158:161], v[198:201], v[28:31]
	v_mfma_f32_16x16x32_bf16 v[20:23], v[150:153], v[208:211], v[20:23]
	v_mfma_f32_16x16x32_bf16 v[12:15], v[158:161], v[208:211], v[12:15]
	v_mfma_f32_16x16x32_bf16 v[48:51], v[162:165], v[178:181], v[48:51]
	v_mfma_f32_16x16x32_bf16 v[40:43], v[170:173], v[178:181], v[40:43]
	v_mfma_f32_16x16x32_bf16 v[32:35], v[162:165], v[186:189], v[32:35]
	v_mfma_f32_16x16x32_bf16 v[24:27], v[170:173], v[186:189], v[24:27]
	v_mfma_f32_16x16x32_bf16 v[16:19], v[162:165], v[194:197], v[16:19]
	v_mfma_f32_16x16x32_bf16 v[8:11], v[170:173], v[194:197], v[8:11]
	v_mfma_f32_16x16x32_bf16 v[4:7], v[162:165], v[202:205], v[4:7]
	v_mfma_f32_16x16x32_bf16 v[0:3], v[170:173], v[202:205], v[0:3]
	v_mfma_f32_16x16x32_bf16 v[48:51], v[166:169], v[182:185], v[48:51]
	v_mfma_f32_16x16x32_bf16 v[40:43], v[174:177], v[182:185], v[40:43]
	v_mfma_f32_16x16x32_bf16 v[32:35], v[166:169], v[190:193], v[32:35]
	v_mfma_f32_16x16x32_bf16 v[24:27], v[174:177], v[190:193], v[24:27]
	v_mfma_f32_16x16x32_bf16 v[16:19], v[166:169], v[198:201], v[16:19]
	v_mfma_f32_16x16x32_bf16 v[8:11], v[174:177], v[198:201], v[8:11]
	v_mfma_f32_16x16x32_bf16 v[4:7], v[166:169], v[208:211], v[4:7]
	v_mfma_f32_16x16x32_bf16 v[0:3], v[174:177], v[208:211], v[0:3]
	s_barrier
	v_add_u32_e32 v158, s49, v143
	v_add_u32_e32 v174, s54, v143
	ds_read_b128 v[146:149], v158
	ds_read_b128 v[150:153], v158 offset:1024
	ds_read_b128 v[154:157], v158 offset:2048
	ds_read_b128 v[158:161], v158 offset:3072
	ds_read_b128 v[162:165], v174
	ds_read_b128 v[166:169], v174 offset:1024
	ds_read_b128 v[170:173], v174 offset:2048
	ds_read_b128 v[174:177], v174 offset:3072
	s_add_u32 s24, s24, 0x80000
	s_addc_u32 s25, s25, 0
	s_mov_b32 m0, s38
	v_lshl_add_u64 v[220:221], s[24:25], 0, v[134:135]
	ds_read_b128 v[178:181], v145 offset:32768
	ds_read_b128 v[182:185], v145 offset:33792
	ds_read_b128 v[186:189], v145 offset:34816
	ds_read_b128 v[190:193], v145 offset:35840
	ds_read_b128 v[194:197], v145 offset:36864
	ds_read_b128 v[198:201], v145 offset:37888
	ds_read_b128 v[202:205], v145 offset:38912
	ds_read_b128 v[208:211], v145 offset:39936
	global_load_lds_dwordx4 v[220:221], off
	v_lshl_add_u64 v[220:221], s[24:25], 0, v[132:133]
	s_mov_b32 m0, s39
	s_nop 0
	global_load_lds_dwordx4 v[220:221], off
	s_waitcnt vmcnt(8)
	s_waitcnt lgkmcnt(0)
	s_barrier
	s_waitcnt lgkmcnt(0)
	v_mfma_f32_16x16x32_bf16 v[124:127], v[146:149], v[178:181], v[124:127]
	v_mfma_f32_16x16x32_bf16 v[120:123], v[154:157], v[178:181], v[120:123]
	v_mfma_f32_16x16x32_bf16 v[116:119], v[146:149], v[186:189], v[116:119]
	v_mfma_f32_16x16x32_bf16 v[108:111], v[154:157], v[186:189], v[108:111]
	v_mfma_f32_16x16x32_bf16 v[100:103], v[146:149], v[194:197], v[100:103]
	v_mfma_f32_16x16x32_bf16 v[92:95], v[154:157], v[194:197], v[92:95]
	v_mfma_f32_16x16x32_bf16 v[84:87], v[146:149], v[202:205], v[84:87]
	v_mfma_f32_16x16x32_bf16 v[76:79], v[154:157], v[202:205], v[76:79]
	v_mfma_f32_16x16x32_bf16 v[124:127], v[150:153], v[182:185], v[124:127]
	v_mfma_f32_16x16x32_bf16 v[120:123], v[158:161], v[182:185], v[120:123]
	v_mfma_f32_16x16x32_bf16 v[116:119], v[150:153], v[190:193], v[116:119]
	v_mfma_f32_16x16x32_bf16 v[108:111], v[158:161], v[190:193], v[108:111]
	v_mfma_f32_16x16x32_bf16 v[100:103], v[150:153], v[198:201], v[100:103]
	v_mfma_f32_16x16x32_bf16 v[92:95], v[158:161], v[198:201], v[92:95]
	v_mfma_f32_16x16x32_bf16 v[84:87], v[150:153], v[208:211], v[84:87]
	v_mfma_f32_16x16x32_bf16 v[76:79], v[158:161], v[208:211], v[76:79]
	v_mfma_f32_16x16x32_bf16 v[112:115], v[162:165], v[178:181], v[112:115]
	v_mfma_f32_16x16x32_bf16 v[104:107], v[170:173], v[178:181], v[104:107]
	v_mfma_f32_16x16x32_bf16 v[96:99], v[162:165], v[186:189], v[96:99]
	v_mfma_f32_16x16x32_bf16 v[88:91], v[170:173], v[186:189], v[88:91]
	v_mfma_f32_16x16x32_bf16 v[80:83], v[162:165], v[194:197], v[80:83]
	v_mfma_f32_16x16x32_bf16 v[72:75], v[170:173], v[194:197], v[72:75]
	v_mfma_f32_16x16x32_bf16 v[68:71], v[162:165], v[202:205], v[68:71]
	v_mfma_f32_16x16x32_bf16 v[64:67], v[170:173], v[202:205], v[64:67]
	v_mfma_f32_16x16x32_bf16 v[112:115], v[166:169], v[182:185], v[112:115]
	v_mfma_f32_16x16x32_bf16 v[104:107], v[174:177], v[182:185], v[104:107]
	v_mfma_f32_16x16x32_bf16 v[96:99], v[166:169], v[190:193], v[96:99]
	v_mfma_f32_16x16x32_bf16 v[88:91], v[174:177], v[190:193], v[88:91]
	v_mfma_f32_16x16x32_bf16 v[80:83], v[166:169], v[198:201], v[80:83]
	v_mfma_f32_16x16x32_bf16 v[72:75], v[174:177], v[198:201], v[72:75]
	v_mfma_f32_16x16x32_bf16 v[68:71], v[166:169], v[208:211], v[68:71]
	v_mfma_f32_16x16x32_bf16 v[64:67], v[174:177], v[208:211], v[64:67]
	s_barrier
; #define PG8_STAGE(bufoff, gbase, voff) do { _Pragma("unroll") for (int _i = 0; _i < 2; ++_i) \
;         __builtin_amdgcn_global_load_lds((const unsigned*)((const char*)(gbase) + (voff)[_i]), (PG8_LAS unsigned*)(lds + (bufoff) + ldsw + _i * 8192), 16, 0, 0); } while (0)
; #define PG8_LDA(dst, b, h) do { _Pragma("unroll") for (int m = 0; m < 4; ++m) _Pragma("unroll") for (int k = 0; k < 2; ++k) dst[m][k] = *(const PG8_LAS bf16x8*)(lds + PG8_SA(b, h) + aoff + m * 2048 + k * 1024); } while (0)
; #define PG8_WAIT_V(n) asm volatile("s_waitcnt vmcnt(" #n ")" ::: "memory")
; #define PG8_WAIT_L(n) asm volatile("s_waitcnt lgkmcnt(" #n ")" ::: "memory")
; #define PG8_BAR __builtin_amdgcn_s_barrier()
; #define PG8_SCHED __builtin_amdgcn_sched_barrier(0)
; template <class Epi, class Sched, bool ALIGN_EPI = false, bool SP2 = false, bool F8 = false>
; __device__ __forceinline__ void gemm_phase(PG8_LAS unsigned char* lds, const Gemm g, const Sched& S, const Epi& E, int wv) {
;     ...
;             PG8_LDA(At, 1, 1); PG8_STAGE(PG8_SB(1, 0), b3, voffB); PG8_STAGE(PG8_SB(1, 1), b3 + hstepB, voffB); PG8_STAGE(PG8_SA(1, 0), a3, voffA);
;             PG8_WAIT_V(8); PG8_WAIT_L(0); PG8_BAR; PG8_MMA(1, 0, At, B0); PG8_MMA(1, 1, At, B1); PG8_BAR; PG8_SCHED;
	s_mov_b32 m0, s41
	v_lshl_add_u64 v[140:141], v[140:141], 0, s[52:53]
	s_add_u32 s22, s22, 0x80080
	ds_read_b128 v[178:181], v145 offset:49152
	ds_read_b128 v[182:185], v145 offset:50176
	ds_read_b128 v[186:189], v145 offset:51200
	ds_read_b128 v[190:193], v145 offset:52224
	ds_read_b128 v[194:197], v145 offset:53248
	ds_read_b128 v[198:201], v145 offset:54272
	ds_read_b128 v[202:205], v145 offset:55296
	ds_read_b128 v[208:211], v145 offset:56320
	global_load_lds_dwordx4 v[140:141], off
	v_lshl_add_u64 v[140:141], v[214:215], 0, s[52:53]
	s_mov_b32 m0, s42
	s_addc_u32 s23, s23, 0
	global_load_lds_dwordx4 v[140:141], off
	v_lshl_add_u64 v[140:141], s[22:23], 0, v[128:129]
	s_mov_b32 m0, s45
	s_nop 0
	global_load_lds_dwordx4 v[140:141], off
	v_lshl_add_u64 v[140:141], s[22:23], 0, v[130:131]
	s_mov_b32 m0, s46
	s_nop 0
	global_load_lds_dwordx4 v[140:141], off
	v_lshl_add_u64 v[140:141], v[216:217], 0, s[52:53]
	s_mov_b32 m0, s43
	s_nop 0
	global_load_lds_dwordx4 v[140:141], off
	v_lshl_add_u64 v[140:141], v[218:219], 0, s[52:53]
	s_mov_b32 m0, s44
	s_nop 0
	global_load_lds_dwordx4 v[140:141], off
	s_waitcnt vmcnt(8)
	s_waitcnt lgkmcnt(0)
	s_barrier
	s_waitcnt lgkmcnt(0)
	v_mfma_f32_16x16x32_bf16 v[60:63], v[146:149], v[178:181], v[60:63]
	v_mfma_f32_16x16x32_bf16 v[56:59], v[154:157], v[178:181], v[56:59]
	v_mfma_f32_16x16x32_bf16 v[52:55], v[146:149], v[186:189], v[52:55]
	v_mfma_f32_16x16x32_bf16 v[44:47], v[154:157], v[186:189], v[44:47]
	v_mfma_f32_16x16x32_bf16 v[36:39], v[146:149], v[194:197], v[36:39]
	v_mfma_f32_16x16x32_bf16 v[28:31], v[154:157], v[194:197], v[28:31]
	v_mfma_f32_16x16x32_bf16 v[20:23], v[146:149], v[202:205], v[20:23]
	v_mfma_f32_16x16x32_bf16 v[12:15], v[154:157], v[202:205], v[12:15]
	v_mfma_f32_16x16x32_bf16 v[60:63], v[150:153], v[182:185], v[60:63]
	v_mfma_f32_16x16x32_bf16 v[56:59], v[158:161], v[182:185], v[56:59]
	v_mfma_f32_16x16x32_bf16 v[52:55], v[150:153], v[190:193], v[52:55]
	v_mfma_f32_16x16x32_bf16 v[44:47], v[158:161], v[190:193], v[44:47]
	v_mfma_f32_16x16x32_bf16 v[36:39], v[150:153], v[198:201], v[36:39]
	v_mfma_f32_16x16x32_bf16 v[28:31], v[158:161], v[198:201], v[28:31]
	v_mfma_f32_16x16x32_bf16 v[20:23], v[150:153], v[208:211], v[20:23]
	v_mfma_f32_16x16x32_bf16 v[12:15], v[158:161], v[208:211], v[12:15]
	v_mfma_f32_16x16x32_bf16 v[48:51], v[162:165], v[178:181], v[48:51]
	v_mfma_f32_16x16x32_bf16 v[40:43], v[170:173], v[178:181], v[40:43]
	v_mfma_f32_16x16x32_bf16 v[32:35], v[162:165], v[186:189], v[32:35]
	v_mfma_f32_16x16x32_bf16 v[24:27], v[170:173], v[186:189], v[24:27]
	v_mfma_f32_16x16x32_bf16 v[16:19], v[162:165], v[194:197], v[16:19]
	v_mfma_f32_16x16x32_bf16 v[8:11], v[170:173], v[194:197], v[8:11]
	v_mfma_f32_16x16x32_bf16 v[4:7], v[162:165], v[202:205], v[4:7]
	v_mfma_f32_16x16x32_bf16 v[0:3], v[170:173], v[202:205], v[0:3]
	v_mfma_f32_16x16x32_bf16 v[48:51], v[166:169], v[182:185], v[48:51]
	v_mfma_f32_16x16x32_bf16 v[40:43], v[174:177], v[182:185], v[40:43]
	v_mfma_f32_16x16x32_bf16 v[32:35], v[166:169], v[190:193], v[32:35]
	v_mfma_f32_16x16x32_bf16 v[24:27], v[174:177], v[190:193], v[24:27]
	v_mfma_f32_16x16x32_bf16 v[16:19], v[166:169], v[198:201], v[16:19]
	v_mfma_f32_16x16x32_bf16 v[8:11], v[174:177], v[198:201], v[8:11]
	v_mfma_f32_16x16x32_bf16 v[4:7], v[166:169], v[208:211], v[4:7]
	v_mfma_f32_16x16x32_bf16 v[0:3], v[174:177], v[208:211], v[0:3]
	s_barrier
	s_add_i32 s61, s61, 2
	s_add_u32 s20, s20, 0x100
	s_addc_u32 s21, s21, 0
	s_add_u32 s59, s59, 0x100
	s_addc_u32 s60, s60, 0
	s_cmp_gt_u32 s61, 29
	s_cbranch_scc0 .LBB0_846
	s_and_b64 vcc, exec, s[6:7]
	s_cbranch_vccz .LBB0_849
	s_barrier
